# hand-written dn_chain with 8-deep register ring (counted vmcnt), warm lead 13; sample-unit conv loads of layer 0 (sdn, sssm) issued back to back instead of one round trip each
# baseline (speedup 1.0000x reference)
.LBB0_564:
	s_cmp_lt_u32 s21, 14
	s_cbranch_scc1 .LBB0_563
	s_memrealtime s[24:25]
	s_add_i32 s18, s21, -13
	s_mul_hi_u32 s19, s18, 60
	s_mul_i32 s18, s18, 60
	v_mov_b64_e32 v[8:9], s[18:19]
	s_waitcnt lgkmcnt(0)
	s_sub_u32 s24, s24, s2
	s_subb_u32 s25, s25, s3
	v_cmp_ge_u64_e32 vcc, s[24:25], v[8:9]
	s_cbranch_vccnz .LBB0_563

.LBB0_790:
	s_load_dwordx4 s[20:23], s[34:35], 0xe0
	v_mbcnt_lo_u32_b32 v66, -1, 0
	v_mbcnt_hi_u32_b32 v66, -1, v66
	v_readlane_b32 s0, v254, 0
	v_readlane_b32 s1, v254, 4
	s_lshr_b32 s0, s0, 6
	s_and_b32 s7, s1, 31
	s_lshr_b32 s8, s1, 7
	s_bfe_u32 s9, s1, 0x20005
	s_mul_i32 s12, s8, 516
	s_add_u32 s12, s12, s9
	s_lshl_b32 s13, s8, 2
	s_add_u32 s13, s13, s9
	v_lshl_or_b32 v67, s0, 6, v66
	v_and_b32_e32 v68, 15, v66
	v_lshrrev_b32_e32 v69, 4, v66
	v_mov_b32_e32 v70, 0
	v_mov_b32_e32 v71, 0
	v_mov_b32_e32 v72, 0
	v_mov_b32_e32 v73, 0
	v_lshlrev_b32_e32 v74, 4, v67
	ds_write_b128 v74, v[70:73]
	v_lshlrev_b32_e32 v56, 4, v66
	s_lshl_b32 s14, s0, 12
	v_or_b32_e32 v56, s14, v56
	s_lshl_b32 s14, s7, 3
	s_add_u32 s14, s14, s0
	s_lshl_b32 s14, s14, 7
	v_or_b32_e32 v57, s14, v66
	v_lshlrev_b32_e32 v57, 3, v57
	v_add_u32_e32 v57, 0x8000, v57
	s_lshl_b32 s14, s7, 4
	s_add_u32 s14, s14, s0
	s_lshl_b32 s14, s14, 4
	v_or_b32_e32 v58, s14, v68
	v_lshlrev_b32_e32 v58, 5, v58
	v_lshl_or_b32 v58, v69, 3, v58
	v_add_u32_e32 v59, 0x1000, v58
	v_and_b32_e32 v75, 7, v68
	v_lshlrev_b32_e32 v75, 4, v75
	v_lshlrev_b32_e32 v76, 8, v68
	v_lshlrev_b32_e32 v77, 4, v69
	v_or_b32_e32 v78, 0, v77
	v_xor_b32_e32 v78, v78, v75
	v_add_u32_e32 v60, v76, v78
	v_or_b32_e32 v78, 64, v77
	v_xor_b32_e32 v78, v78, v75
	v_add_u32_e32 v61, v76, v78
	v_or_b32_e32 v78, 128, v77
	v_xor_b32_e32 v78, v78, v75
	v_add_u32_e32 v62, v76, v78
	v_or_b32_e32 v78, 192, v77
	v_xor_b32_e32 v78, v78, v75
	v_add_u32_e32 v63, v76, v78
	v_lshlrev_b32_e32 v78, 3, v69
	s_lshl_b32 s14, s0, 5
	v_or_b32_e32 v78, s14, v78
	v_xor_b32_e32 v78, v78, v75
	v_add_u32_e32 v64, v76, v78
	v_mov_b32_e32 v65, 0
	s_waitcnt lgkmcnt(0)
	s_mul_i32 s14, s12, 0x18000
	s_add_u32 s2, s22, s14
	s_addc_u32 s3, s23, 0
	s_add_u32 s2, s2, 0x10000000
	s_addc_u32 s3, s3, 0
	s_lshl_b32 s14, s12, 15
	s_add_u32 s4, s22, s14
	s_addc_u32 s5, s23, 0
	s_add_u32 s4, s4, 0x16100000
	s_addc_u32 s5, s5, 0
	s_mul_i32 s14, s13, 528
	s_add_u32 s16, s22, s14
	s_addc_u32 s17, s23, 0
	s_add_u32 s16, s16, 0x80000
	s_addc_u32 s17, s17, 0
	v_lshlrev_b32_e32 v79, 2, v67
	v_cmp_gt_u32_e32 vcc, 129, v67
	s_and_saveexec_b64 s[18:19], vcc
	global_load_dword v80, v79, s[16:17]
	s_waitcnt vmcnt(0)
	ds_write_b32 v79, v80 offset:16384
	s_mov_b64 exec, s[18:19]
	s_mov_b64 s[10:11], s[2:3]
	global_load_dwordx4 v[154:157], v56, s[10:11] offset:0
	global_load_dwordx4 v[158:161], v56, s[10:11] offset:1024
	global_load_dwordx4 v[162:165], v56, s[10:11] offset:2048
	global_load_dwordx4 v[166:169], v56, s[10:11] offset:3072
	global_load_dwordx2 v[170:171], v57, s[10:11]
	global_load_dwordx2 v[172:173], v57, s[10:11] offset:512
	s_add_u32 s10, s10, 0x60000
	s_addc_u32 s11, s11, 0
	global_load_dwordx4 v[174:177], v56, s[10:11] offset:0
	global_load_dwordx4 v[178:181], v56, s[10:11] offset:1024
	global_load_dwordx4 v[182:185], v56, s[10:11] offset:2048
	global_load_dwordx4 v[186:189], v56, s[10:11] offset:3072
	global_load_dwordx2 v[190:191], v57, s[10:11]
	global_load_dwordx2 v[192:193], v57, s[10:11] offset:512
	s_add_u32 s10, s10, 0x60000
	s_addc_u32 s11, s11, 0
	global_load_dwordx4 v[194:197], v56, s[10:11] offset:0
	global_load_dwordx4 v[198:201], v56, s[10:11] offset:1024
	global_load_dwordx4 v[202:205], v56, s[10:11] offset:2048
	global_load_dwordx4 v[206:209], v56, s[10:11] offset:3072
	global_load_dwordx2 v[210:211], v57, s[10:11]
	global_load_dwordx2 v[212:213], v57, s[10:11] offset:512
	s_add_u32 s10, s10, 0x60000
	s_addc_u32 s11, s11, 0
	global_load_dwordx4 v[214:217], v56, s[10:11] offset:0
	global_load_dwordx4 v[218:221], v56, s[10:11] offset:1024
	global_load_dwordx4 v[222:225], v56, s[10:11] offset:2048
	global_load_dwordx4 v[226:229], v56, s[10:11] offset:3072
	global_load_dwordx2 v[230:231], v57, s[10:11]
	global_load_dwordx2 v[232:233], v57, s[10:11] offset:512
	s_add_u32 s10, s10, 0x60000
	s_addc_u32 s11, s11, 0
	global_load_dwordx4 v[234:237], v56, s[10:11] offset:0
	global_load_dwordx4 v[238:241], v56, s[10:11] offset:1024
	global_load_dwordx4 v[242:245], v56, s[10:11] offset:2048
	global_load_dwordx4 v[246:249], v56, s[10:11] offset:3072
	global_load_dwordx2 v[250:251], v57, s[10:11]
	global_load_dwordx2 v[252:253], v57, s[10:11] offset:512
	s_add_u32 s10, s10, 0x60000
	s_addc_u32 s11, s11, 0
	global_load_dwordx4 v[90:93], v56, s[10:11] offset:0
	global_load_dwordx4 v[94:97], v56, s[10:11] offset:1024
	global_load_dwordx4 v[98:101], v56, s[10:11] offset:2048
	global_load_dwordx4 v[102:105], v56, s[10:11] offset:3072
	global_load_dwordx2 v[106:107], v57, s[10:11]
	global_load_dwordx2 v[108:109], v57, s[10:11] offset:512
	s_add_u32 s10, s10, 0x60000
	s_addc_u32 s11, s11, 0
	global_load_dwordx4 v[110:113], v56, s[10:11] offset:0
	global_load_dwordx4 v[114:117], v56, s[10:11] offset:1024
	global_load_dwordx4 v[118:121], v56, s[10:11] offset:2048
	global_load_dwordx4 v[122:125], v56, s[10:11] offset:3072
	global_load_dwordx2 v[126:127], v57, s[10:11]
	global_load_dwordx2 v[128:129], v57, s[10:11] offset:512
	s_add_u32 s10, s10, 0x60000
	s_addc_u32 s11, s11, 0
	global_load_dwordx4 v[130:133], v56, s[10:11] offset:0
	global_load_dwordx4 v[134:137], v56, s[10:11] offset:1024
	global_load_dwordx4 v[138:141], v56, s[10:11] offset:2048
	global_load_dwordx4 v[142:145], v56, s[10:11] offset:3072
	global_load_dwordx2 v[146:147], v57, s[10:11]
	global_load_dwordx2 v[148:149], v57, s[10:11] offset:512
	v_mov_b32_e32 v0, 0
	v_mov_b32_e32 v1, 0
	v_mov_b32_e32 v2, 0
	v_mov_b32_e32 v3, 0
	v_mov_b32_e32 v4, 0
	v_mov_b32_e32 v5, 0
	v_mov_b32_e32 v6, 0
	v_mov_b32_e32 v7, 0
	v_mov_b32_e32 v8, 0
	v_mov_b32_e32 v9, 0
	v_mov_b32_e32 v10, 0
	v_mov_b32_e32 v11, 0
	s_mov_b32 s6, 0
	s_waitcnt lgkmcnt(0)
	s_barrier
	global_store_dwordx2 v58, v[8:9], s[4:5]
	global_store_dwordx2 v59, v[10:11], s[4:5]
	ds_read_b32 v12, v65 offset:16384
	ds_read_b128 v[24:27], v60 offset:0
	ds_read_b128 v[28:31], v60 offset:4096
	ds_read_b128 v[32:35], v61 offset:0
	ds_read_b128 v[36:39], v61 offset:4096
	ds_read_b128 v[40:43], v62 offset:0
	ds_read_b128 v[44:47], v62 offset:4096
	ds_read_b128 v[48:51], v63 offset:0
	ds_read_b128 v[52:55], v63 offset:4096
	s_add_u32 s4, s4, 0x20000
	s_addc_u32 s5, s5, 0
	s_waitcnt vmcnt(44)
	v_lshlrev_b32_e32 v14, 16, v170
	v_and_b32_e32 v15, 0xffff0000, v170
	v_lshlrev_b32_e32 v16, 16, v171
	v_and_b32_e32 v17, 0xffff0000, v171
	v_lshlrev_b32_e32 v18, 16, v172
	v_and_b32_e32 v19, 0xffff0000, v172
	v_lshlrev_b32_e32 v20, 16, v173
	v_and_b32_e32 v21, 0xffff0000, v173
	s_waitcnt lgkmcnt(8)
	v_pk_fma_f32 v[0:1], v[0:1], v[12:13], v[14:15] op_sel_hi:[1,0,1]
	v_pk_fma_f32 v[2:3], v[2:3], v[12:13], v[16:17] op_sel_hi:[1,0,1]
	v_pk_fma_f32 v[4:5], v[4:5], v[12:13], v[18:19] op_sel_hi:[1,0,1]
	v_pk_fma_f32 v[6:7], v[6:7], v[12:13], v[20:21] op_sel_hi:[1,0,1]
	s_waitcnt lgkmcnt(7)
	v_mfma_f32_16x16x32_bf16 v[0:3], v[154:157], v[24:27], v[0:3]
	s_waitcnt lgkmcnt(6)
	v_mfma_f32_16x16x32_bf16 v[4:7], v[154:157], v[28:31], v[4:7]
	s_waitcnt lgkmcnt(5)
	v_mfma_f32_16x16x32_bf16 v[0:3], v[158:161], v[32:35], v[0:3]
	s_waitcnt lgkmcnt(4)
	v_mfma_f32_16x16x32_bf16 v[4:7], v[158:161], v[36:39], v[4:7]
	s_waitcnt lgkmcnt(3)
	v_mfma_f32_16x16x32_bf16 v[0:3], v[162:165], v[40:43], v[0:3]
	s_waitcnt lgkmcnt(2)
	v_mfma_f32_16x16x32_bf16 v[4:7], v[162:165], v[44:47], v[4:7]
	s_waitcnt lgkmcnt(1)
	v_mfma_f32_16x16x32_bf16 v[0:3], v[166:169], v[48:51], v[0:3]
	s_waitcnt lgkmcnt(0)
	v_mfma_f32_16x16x32_bf16 v[4:7], v[166:169], v[52:55], v[4:7]
	s_add_u32 s7, s6, 8
	s_min_u32 s7, s7, 0x80
	s_mul_i32 s7, s7, 0x60000
	s_add_u32 s10, s2, s7
	s_addc_u32 s11, s3, 0
	global_load_dwordx4 v[154:157], v56, s[10:11] offset:0
	global_load_dwordx4 v[158:161], v56, s[10:11] offset:1024
	global_load_dwordx4 v[162:165], v56, s[10:11] offset:2048
	global_load_dwordx4 v[166:169], v56, s[10:11] offset:3072
	global_load_dwordx2 v[170:171], v57, s[10:11]
	global_load_dwordx2 v[172:173], v57, s[10:11] offset:512
	v_cvt_pk_bf16_f32 v8, v0, v1
	v_cvt_pk_bf16_f32 v9, v2, v3
	v_cvt_pk_bf16_f32 v10, v4, v5
	v_cvt_pk_bf16_f32 v11, v6, v7
	ds_write_b64 v64, v[8:9] offset:8192
	ds_write_b64 v64, v[10:11] offset:12288
	s_waitcnt lgkmcnt(0)
	s_barrier
	global_store_dwordx2 v58, v[8:9], s[4:5]
	global_store_dwordx2 v59, v[10:11], s[4:5]
	ds_read_b32 v12, v65 offset:16388
	ds_read_b128 v[24:27], v60 offset:8192
	ds_read_b128 v[28:31], v60 offset:12288
	ds_read_b128 v[32:35], v61 offset:8192
	ds_read_b128 v[36:39], v61 offset:12288
	ds_read_b128 v[40:43], v62 offset:8192
	ds_read_b128 v[44:47], v62 offset:12288
	ds_read_b128 v[48:51], v63 offset:8192
	ds_read_b128 v[52:55], v63 offset:12288
	s_add_u32 s4, s4, 0x20000
	s_addc_u32 s5, s5, 0
	s_waitcnt vmcnt(46)
	v_lshlrev_b32_e32 v14, 16, v190
	v_and_b32_e32 v15, 0xffff0000, v190
	v_lshlrev_b32_e32 v16, 16, v191
	v_and_b32_e32 v17, 0xffff0000, v191
	v_lshlrev_b32_e32 v18, 16, v192
	v_and_b32_e32 v19, 0xffff0000, v192
	v_lshlrev_b32_e32 v20, 16, v193
	v_and_b32_e32 v21, 0xffff0000, v193
	s_waitcnt lgkmcnt(8)
	v_pk_fma_f32 v[0:1], v[0:1], v[12:13], v[14:15] op_sel_hi:[1,0,1]
	v_pk_fma_f32 v[2:3], v[2:3], v[12:13], v[16:17] op_sel_hi:[1,0,1]
	v_pk_fma_f32 v[4:5], v[4:5], v[12:13], v[18:19] op_sel_hi:[1,0,1]
	v_pk_fma_f32 v[6:7], v[6:7], v[12:13], v[20:21] op_sel_hi:[1,0,1]
	s_waitcnt lgkmcnt(7)
	v_mfma_f32_16x16x32_bf16 v[0:3], v[174:177], v[24:27], v[0:3]
	s_waitcnt lgkmcnt(6)
	v_mfma_f32_16x16x32_bf16 v[4:7], v[174:177], v[28:31], v[4:7]
	s_waitcnt lgkmcnt(5)
	v_mfma_f32_16x16x32_bf16 v[0:3], v[178:181], v[32:35], v[0:3]
	s_waitcnt lgkmcnt(4)
	v_mfma_f32_16x16x32_bf16 v[4:7], v[178:181], v[36:39], v[4:7]
	s_waitcnt lgkmcnt(3)
	v_mfma_f32_16x16x32_bf16 v[0:3], v[182:185], v[40:43], v[0:3]
	s_waitcnt lgkmcnt(2)
	v_mfma_f32_16x16x32_bf16 v[4:7], v[182:185], v[44:47], v[4:7]
	s_waitcnt lgkmcnt(1)
	v_mfma_f32_16x16x32_bf16 v[0:3], v[186:189], v[48:51], v[0:3]
	s_waitcnt lgkmcnt(0)
	v_mfma_f32_16x16x32_bf16 v[4:7], v[186:189], v[52:55], v[4:7]
	s_add_u32 s7, s6, 9
	s_min_u32 s7, s7, 0x80
	s_mul_i32 s7, s7, 0x60000
	s_add_u32 s10, s2, s7
	s_addc_u32 s11, s3, 0
	global_load_dwordx4 v[174:177], v56, s[10:11] offset:0
	global_load_dwordx4 v[178:181], v56, s[10:11] offset:1024
	global_load_dwordx4 v[182:185], v56, s[10:11] offset:2048
	global_load_dwordx4 v[186:189], v56, s[10:11] offset:3072
	global_load_dwordx2 v[190:191], v57, s[10:11]
	global_load_dwordx2 v[192:193], v57, s[10:11] offset:512
	v_cvt_pk_bf16_f32 v8, v0, v1
	v_cvt_pk_bf16_f32 v9, v2, v3
	v_cvt_pk_bf16_f32 v10, v4, v5
	v_cvt_pk_bf16_f32 v11, v6, v7
	ds_write_b64 v64, v[8:9] offset:0
	ds_write_b64 v64, v[10:11] offset:4096
	s_waitcnt lgkmcnt(0)
	s_barrier
	global_store_dwordx2 v58, v[8:9], s[4:5]
	global_store_dwordx2 v59, v[10:11], s[4:5]
	ds_read_b32 v12, v65 offset:16392
	ds_read_b128 v[24:27], v60 offset:0
	ds_read_b128 v[28:31], v60 offset:4096
	ds_read_b128 v[32:35], v61 offset:0
	ds_read_b128 v[36:39], v61 offset:4096
	ds_read_b128 v[40:43], v62 offset:0
	ds_read_b128 v[44:47], v62 offset:4096
	ds_read_b128 v[48:51], v63 offset:0
	ds_read_b128 v[52:55], v63 offset:4096
	s_add_u32 s4, s4, 0x20000
	s_addc_u32 s5, s5, 0
	s_waitcnt vmcnt(48)
	v_lshlrev_b32_e32 v14, 16, v210
	v_and_b32_e32 v15, 0xffff0000, v210
	v_lshlrev_b32_e32 v16, 16, v211
	v_and_b32_e32 v17, 0xffff0000, v211
	v_lshlrev_b32_e32 v18, 16, v212
	v_and_b32_e32 v19, 0xffff0000, v212
	v_lshlrev_b32_e32 v20, 16, v213
	v_and_b32_e32 v21, 0xffff0000, v213
	s_waitcnt lgkmcnt(8)
	v_pk_fma_f32 v[0:1], v[0:1], v[12:13], v[14:15] op_sel_hi:[1,0,1]
	v_pk_fma_f32 v[2:3], v[2:3], v[12:13], v[16:17] op_sel_hi:[1,0,1]
	v_pk_fma_f32 v[4:5], v[4:5], v[12:13], v[18:19] op_sel_hi:[1,0,1]
	v_pk_fma_f32 v[6:7], v[6:7], v[12:13], v[20:21] op_sel_hi:[1,0,1]
	s_waitcnt lgkmcnt(7)
	v_mfma_f32_16x16x32_bf16 v[0:3], v[194:197], v[24:27], v[0:3]
	s_waitcnt lgkmcnt(6)
	v_mfma_f32_16x16x32_bf16 v[4:7], v[194:197], v[28:31], v[4:7]
	s_waitcnt lgkmcnt(5)
	v_mfma_f32_16x16x32_bf16 v[0:3], v[198:201], v[32:35], v[0:3]
	s_waitcnt lgkmcnt(4)
	v_mfma_f32_16x16x32_bf16 v[4:7], v[198:201], v[36:39], v[4:7]
	s_waitcnt lgkmcnt(3)
	v_mfma_f32_16x16x32_bf16 v[0:3], v[202:205], v[40:43], v[0:3]
	s_waitcnt lgkmcnt(2)
	v_mfma_f32_16x16x32_bf16 v[4:7], v[202:205], v[44:47], v[4:7]
	s_waitcnt lgkmcnt(1)
	v_mfma_f32_16x16x32_bf16 v[0:3], v[206:209], v[48:51], v[0:3]
	s_waitcnt lgkmcnt(0)
	v_mfma_f32_16x16x32_bf16 v[4:7], v[206:209], v[52:55], v[4:7]
	s_add_u32 s7, s6, 10
	s_min_u32 s7, s7, 0x80
	s_mul_i32 s7, s7, 0x60000
	s_add_u32 s10, s2, s7
	s_addc_u32 s11, s3, 0
	global_load_dwordx4 v[194:197], v56, s[10:11] offset:0
	global_load_dwordx4 v[198:201], v56, s[10:11] offset:1024
	global_load_dwordx4 v[202:205], v56, s[10:11] offset:2048
	global_load_dwordx4 v[206:209], v56, s[10:11] offset:3072
	global_load_dwordx2 v[210:211], v57, s[10:11]
	global_load_dwordx2 v[212:213], v57, s[10:11] offset:512
	v_cvt_pk_bf16_f32 v8, v0, v1
	v_cvt_pk_bf16_f32 v9, v2, v3
	v_cvt_pk_bf16_f32 v10, v4, v5
	v_cvt_pk_bf16_f32 v11, v6, v7
	ds_write_b64 v64, v[8:9] offset:8192
	ds_write_b64 v64, v[10:11] offset:12288
	s_waitcnt lgkmcnt(0)
	s_barrier
	global_store_dwordx2 v58, v[8:9], s[4:5]
	global_store_dwordx2 v59, v[10:11], s[4:5]
	ds_read_b32 v12, v65 offset:16396
	ds_read_b128 v[24:27], v60 offset:8192
	ds_read_b128 v[28:31], v60 offset:12288
	ds_read_b128 v[32:35], v61 offset:8192
	ds_read_b128 v[36:39], v61 offset:12288
	ds_read_b128 v[40:43], v62 offset:8192
	ds_read_b128 v[44:47], v62 offset:12288
	ds_read_b128 v[48:51], v63 offset:8192
	ds_read_b128 v[52:55], v63 offset:12288
	s_add_u32 s4, s4, 0x20000
	s_addc_u32 s5, s5, 0
	s_waitcnt vmcnt(50)
	v_lshlrev_b32_e32 v14, 16, v230
	v_and_b32_e32 v15, 0xffff0000, v230
	v_lshlrev_b32_e32 v16, 16, v231
	v_and_b32_e32 v17, 0xffff0000, v231
	v_lshlrev_b32_e32 v18, 16, v232
	v_and_b32_e32 v19, 0xffff0000, v232
	v_lshlrev_b32_e32 v20, 16, v233
	v_and_b32_e32 v21, 0xffff0000, v233
	s_waitcnt lgkmcnt(8)
	v_pk_fma_f32 v[0:1], v[0:1], v[12:13], v[14:15] op_sel_hi:[1,0,1]
	v_pk_fma_f32 v[2:3], v[2:3], v[12:13], v[16:17] op_sel_hi:[1,0,1]
	v_pk_fma_f32 v[4:5], v[4:5], v[12:13], v[18:19] op_sel_hi:[1,0,1]
	v_pk_fma_f32 v[6:7], v[6:7], v[12:13], v[20:21] op_sel_hi:[1,0,1]
	s_waitcnt lgkmcnt(7)
	v_mfma_f32_16x16x32_bf16 v[0:3], v[214:217], v[24:27], v[0:3]
	s_waitcnt lgkmcnt(6)
	v_mfma_f32_16x16x32_bf16 v[4:7], v[214:217], v[28:31], v[4:7]
	s_waitcnt lgkmcnt(5)
	v_mfma_f32_16x16x32_bf16 v[0:3], v[218:221], v[32:35], v[0:3]
	s_waitcnt lgkmcnt(4)
	v_mfma_f32_16x16x32_bf16 v[4:7], v[218:221], v[36:39], v[4:7]
	s_waitcnt lgkmcnt(3)
	v_mfma_f32_16x16x32_bf16 v[0:3], v[222:225], v[40:43], v[0:3]
	s_waitcnt lgkmcnt(2)
	v_mfma_f32_16x16x32_bf16 v[4:7], v[222:225], v[44:47], v[4:7]
	s_waitcnt lgkmcnt(1)
	v_mfma_f32_16x16x32_bf16 v[0:3], v[226:229], v[48:51], v[0:3]
	s_waitcnt lgkmcnt(0)
	v_mfma_f32_16x16x32_bf16 v[4:7], v[226:229], v[52:55], v[4:7]
	s_add_u32 s7, s6, 11
	s_min_u32 s7, s7, 0x80
	s_mul_i32 s7, s7, 0x60000
	s_add_u32 s10, s2, s7
	s_addc_u32 s11, s3, 0
	global_load_dwordx4 v[214:217], v56, s[10:11] offset:0
	global_load_dwordx4 v[218:221], v56, s[10:11] offset:1024
	global_load_dwordx4 v[222:225], v56, s[10:11] offset:2048
	global_load_dwordx4 v[226:229], v56, s[10:11] offset:3072
	global_load_dwordx2 v[230:231], v57, s[10:11]
	global_load_dwordx2 v[232:233], v57, s[10:11] offset:512
	v_cvt_pk_bf16_f32 v8, v0, v1
	v_cvt_pk_bf16_f32 v9, v2, v3
	v_cvt_pk_bf16_f32 v10, v4, v5
	v_cvt_pk_bf16_f32 v11, v6, v7
	ds_write_b64 v64, v[8:9] offset:0
	ds_write_b64 v64, v[10:11] offset:4096
	s_waitcnt lgkmcnt(0)
	s_barrier
	global_store_dwordx2 v58, v[8:9], s[4:5]
	global_store_dwordx2 v59, v[10:11], s[4:5]
	ds_read_b32 v12, v65 offset:16400
	ds_read_b128 v[24:27], v60 offset:0
	ds_read_b128 v[28:31], v60 offset:4096
	ds_read_b128 v[32:35], v61 offset:0
	ds_read_b128 v[36:39], v61 offset:4096
	ds_read_b128 v[40:43], v62 offset:0
	ds_read_b128 v[44:47], v62 offset:4096
	ds_read_b128 v[48:51], v63 offset:0
	ds_read_b128 v[52:55], v63 offset:4096
	s_add_u32 s4, s4, 0x20000
	s_addc_u32 s5, s5, 0
	s_waitcnt vmcnt(52)
	v_lshlrev_b32_e32 v14, 16, v250
	v_and_b32_e32 v15, 0xffff0000, v250
	v_lshlrev_b32_e32 v16, 16, v251
	v_and_b32_e32 v17, 0xffff0000, v251
	v_lshlrev_b32_e32 v18, 16, v252
	v_and_b32_e32 v19, 0xffff0000, v252
	v_lshlrev_b32_e32 v20, 16, v253
	v_and_b32_e32 v21, 0xffff0000, v253
	s_waitcnt lgkmcnt(8)
	v_pk_fma_f32 v[0:1], v[0:1], v[12:13], v[14:15] op_sel_hi:[1,0,1]
	v_pk_fma_f32 v[2:3], v[2:3], v[12:13], v[16:17] op_sel_hi:[1,0,1]
	v_pk_fma_f32 v[4:5], v[4:5], v[12:13], v[18:19] op_sel_hi:[1,0,1]
	v_pk_fma_f32 v[6:7], v[6:7], v[12:13], v[20:21] op_sel_hi:[1,0,1]
	s_waitcnt lgkmcnt(7)
	v_mfma_f32_16x16x32_bf16 v[0:3], v[234:237], v[24:27], v[0:3]
	s_waitcnt lgkmcnt(6)
	v_mfma_f32_16x16x32_bf16 v[4:7], v[234:237], v[28:31], v[4:7]
	s_waitcnt lgkmcnt(5)
	v_mfma_f32_16x16x32_bf16 v[0:3], v[238:241], v[32:35], v[0:3]
	s_waitcnt lgkmcnt(4)
	v_mfma_f32_16x16x32_bf16 v[4:7], v[238:241], v[36:39], v[4:7]
	s_waitcnt lgkmcnt(3)
	v_mfma_f32_16x16x32_bf16 v[0:3], v[242:245], v[40:43], v[0:3]
	s_waitcnt lgkmcnt(2)
	v_mfma_f32_16x16x32_bf16 v[4:7], v[242:245], v[44:47], v[4:7]
	s_waitcnt lgkmcnt(1)
	v_mfma_f32_16x16x32_bf16 v[0:3], v[246:249], v[48:51], v[0:3]
	s_waitcnt lgkmcnt(0)
	v_mfma_f32_16x16x32_bf16 v[4:7], v[246:249], v[52:55], v[4:7]
	s_add_u32 s7, s6, 12
	s_min_u32 s7, s7, 0x80
	s_mul_i32 s7, s7, 0x60000
	s_add_u32 s10, s2, s7
	s_addc_u32 s11, s3, 0
	global_load_dwordx4 v[234:237], v56, s[10:11] offset:0
	global_load_dwordx4 v[238:241], v56, s[10:11] offset:1024
	global_load_dwordx4 v[242:245], v56, s[10:11] offset:2048
	global_load_dwordx4 v[246:249], v56, s[10:11] offset:3072
	global_load_dwordx2 v[250:251], v57, s[10:11]
	global_load_dwordx2 v[252:253], v57, s[10:11] offset:512
	v_cvt_pk_bf16_f32 v8, v0, v1
	v_cvt_pk_bf16_f32 v9, v2, v3
	v_cvt_pk_bf16_f32 v10, v4, v5
	v_cvt_pk_bf16_f32 v11, v6, v7
	ds_write_b64 v64, v[8:9] offset:8192
	ds_write_b64 v64, v[10:11] offset:12288
	s_waitcnt lgkmcnt(0)
	s_barrier
	global_store_dwordx2 v58, v[8:9], s[4:5]
	global_store_dwordx2 v59, v[10:11], s[4:5]
	ds_read_b32 v12, v65 offset:16404
	ds_read_b128 v[24:27], v60 offset:8192
	ds_read_b128 v[28:31], v60 offset:12288
	ds_read_b128 v[32:35], v61 offset:8192
	ds_read_b128 v[36:39], v61 offset:12288
	ds_read_b128 v[40:43], v62 offset:8192
	ds_read_b128 v[44:47], v62 offset:12288
	ds_read_b128 v[48:51], v63 offset:8192
	ds_read_b128 v[52:55], v63 offset:12288
	s_add_u32 s4, s4, 0x20000
	s_addc_u32 s5, s5, 0
	s_waitcnt vmcnt(54)
	v_lshlrev_b32_e32 v14, 16, v106
	v_and_b32_e32 v15, 0xffff0000, v106
	v_lshlrev_b32_e32 v16, 16, v107
	v_and_b32_e32 v17, 0xffff0000, v107
	v_lshlrev_b32_e32 v18, 16, v108
	v_and_b32_e32 v19, 0xffff0000, v108
	v_lshlrev_b32_e32 v20, 16, v109
	v_and_b32_e32 v21, 0xffff0000, v109
	s_waitcnt lgkmcnt(8)
	v_pk_fma_f32 v[0:1], v[0:1], v[12:13], v[14:15] op_sel_hi:[1,0,1]
	v_pk_fma_f32 v[2:3], v[2:3], v[12:13], v[16:17] op_sel_hi:[1,0,1]
	v_pk_fma_f32 v[4:5], v[4:5], v[12:13], v[18:19] op_sel_hi:[1,0,1]
	v_pk_fma_f32 v[6:7], v[6:7], v[12:13], v[20:21] op_sel_hi:[1,0,1]
	s_waitcnt lgkmcnt(7)
	v_mfma_f32_16x16x32_bf16 v[0:3], v[90:93], v[24:27], v[0:3]
	s_waitcnt lgkmcnt(6)
	v_mfma_f32_16x16x32_bf16 v[4:7], v[90:93], v[28:31], v[4:7]
	s_waitcnt lgkmcnt(5)
	v_mfma_f32_16x16x32_bf16 v[0:3], v[94:97], v[32:35], v[0:3]
	s_waitcnt lgkmcnt(4)
	v_mfma_f32_16x16x32_bf16 v[4:7], v[94:97], v[36:39], v[4:7]
	s_waitcnt lgkmcnt(3)
	v_mfma_f32_16x16x32_bf16 v[0:3], v[98:101], v[40:43], v[0:3]
	s_waitcnt lgkmcnt(2)
	v_mfma_f32_16x16x32_bf16 v[4:7], v[98:101], v[44:47], v[4:7]
	s_waitcnt lgkmcnt(1)
	v_mfma_f32_16x16x32_bf16 v[0:3], v[102:105], v[48:51], v[0:3]
	s_waitcnt lgkmcnt(0)
	v_mfma_f32_16x16x32_bf16 v[4:7], v[102:105], v[52:55], v[4:7]
	s_add_u32 s7, s6, 13
	s_min_u32 s7, s7, 0x80
	s_mul_i32 s7, s7, 0x60000
	s_add_u32 s10, s2, s7
	s_addc_u32 s11, s3, 0
	global_load_dwordx4 v[90:93], v56, s[10:11] offset:0
	global_load_dwordx4 v[94:97], v56, s[10:11] offset:1024
	global_load_dwordx4 v[98:101], v56, s[10:11] offset:2048
	global_load_dwordx4 v[102:105], v56, s[10:11] offset:3072
	global_load_dwordx2 v[106:107], v57, s[10:11]
	global_load_dwordx2 v[108:109], v57, s[10:11] offset:512
	v_cvt_pk_bf16_f32 v8, v0, v1
	v_cvt_pk_bf16_f32 v9, v2, v3
	v_cvt_pk_bf16_f32 v10, v4, v5
	v_cvt_pk_bf16_f32 v11, v6, v7
	ds_write_b64 v64, v[8:9] offset:0
	ds_write_b64 v64, v[10:11] offset:4096
	s_waitcnt lgkmcnt(0)
	s_barrier
	global_store_dwordx2 v58, v[8:9], s[4:5]
	global_store_dwordx2 v59, v[10:11], s[4:5]
	ds_read_b32 v12, v65 offset:16408
	ds_read_b128 v[24:27], v60 offset:0
	ds_read_b128 v[28:31], v60 offset:4096
	ds_read_b128 v[32:35], v61 offset:0
	ds_read_b128 v[36:39], v61 offset:4096
	ds_read_b128 v[40:43], v62 offset:0
	ds_read_b128 v[44:47], v62 offset:4096
	ds_read_b128 v[48:51], v63 offset:0
	ds_read_b128 v[52:55], v63 offset:4096
	s_add_u32 s4, s4, 0x20000
	s_addc_u32 s5, s5, 0
	s_waitcnt vmcnt(56)
	v_lshlrev_b32_e32 v14, 16, v126
	v_and_b32_e32 v15, 0xffff0000, v126
	v_lshlrev_b32_e32 v16, 16, v127
	v_and_b32_e32 v17, 0xffff0000, v127
	v_lshlrev_b32_e32 v18, 16, v128
	v_and_b32_e32 v19, 0xffff0000, v128
	v_lshlrev_b32_e32 v20, 16, v129
	v_and_b32_e32 v21, 0xffff0000, v129
	s_waitcnt lgkmcnt(8)
	v_pk_fma_f32 v[0:1], v[0:1], v[12:13], v[14:15] op_sel_hi:[1,0,1]
	v_pk_fma_f32 v[2:3], v[2:3], v[12:13], v[16:17] op_sel_hi:[1,0,1]
	v_pk_fma_f32 v[4:5], v[4:5], v[12:13], v[18:19] op_sel_hi:[1,0,1]
	v_pk_fma_f32 v[6:7], v[6:7], v[12:13], v[20:21] op_sel_hi:[1,0,1]
	s_waitcnt lgkmcnt(7)
	v_mfma_f32_16x16x32_bf16 v[0:3], v[110:113], v[24:27], v[0:3]
	s_waitcnt lgkmcnt(6)
	v_mfma_f32_16x16x32_bf16 v[4:7], v[110:113], v[28:31], v[4:7]
	s_waitcnt lgkmcnt(5)
	v_mfma_f32_16x16x32_bf16 v[0:3], v[114:117], v[32:35], v[0:3]
	s_waitcnt lgkmcnt(4)
	v_mfma_f32_16x16x32_bf16 v[4:7], v[114:117], v[36:39], v[4:7]
	s_waitcnt lgkmcnt(3)
	v_mfma_f32_16x16x32_bf16 v[0:3], v[118:121], v[40:43], v[0:3]
	s_waitcnt lgkmcnt(2)
	v_mfma_f32_16x16x32_bf16 v[4:7], v[118:121], v[44:47], v[4:7]
	s_waitcnt lgkmcnt(1)
	v_mfma_f32_16x16x32_bf16 v[0:3], v[122:125], v[48:51], v[0:3]
	s_waitcnt lgkmcnt(0)
	v_mfma_f32_16x16x32_bf16 v[4:7], v[122:125], v[52:55], v[4:7]
	s_add_u32 s7, s6, 14
	s_min_u32 s7, s7, 0x80
	s_mul_i32 s7, s7, 0x60000
	s_add_u32 s10, s2, s7
	s_addc_u32 s11, s3, 0
	global_load_dwordx4 v[110:113], v56, s[10:11] offset:0
	global_load_dwordx4 v[114:117], v56, s[10:11] offset:1024
	global_load_dwordx4 v[118:121], v56, s[10:11] offset:2048
	global_load_dwordx4 v[122:125], v56, s[10:11] offset:3072
	global_load_dwordx2 v[126:127], v57, s[10:11]
	global_load_dwordx2 v[128:129], v57, s[10:11] offset:512
	v_cvt_pk_bf16_f32 v8, v0, v1
	v_cvt_pk_bf16_f32 v9, v2, v3
	v_cvt_pk_bf16_f32 v10, v4, v5
	v_cvt_pk_bf16_f32 v11, v6, v7
	ds_write_b64 v64, v[8:9] offset:8192
	ds_write_b64 v64, v[10:11] offset:12288
	s_waitcnt lgkmcnt(0)
	s_barrier
	global_store_dwordx2 v58, v[8:9], s[4:5]
	global_store_dwordx2 v59, v[10:11], s[4:5]
	ds_read_b32 v12, v65 offset:16412
	ds_read_b128 v[24:27], v60 offset:8192
	ds_read_b128 v[28:31], v60 offset:12288
	ds_read_b128 v[32:35], v61 offset:8192
	ds_read_b128 v[36:39], v61 offset:12288
	ds_read_b128 v[40:43], v62 offset:8192
	ds_read_b128 v[44:47], v62 offset:12288
	ds_read_b128 v[48:51], v63 offset:8192
	ds_read_b128 v[52:55], v63 offset:12288
	s_add_u32 s4, s4, 0x20000
	s_addc_u32 s5, s5, 0
	s_waitcnt vmcnt(58)
	v_lshlrev_b32_e32 v14, 16, v146
	v_and_b32_e32 v15, 0xffff0000, v146
	v_lshlrev_b32_e32 v16, 16, v147
	v_and_b32_e32 v17, 0xffff0000, v147
	v_lshlrev_b32_e32 v18, 16, v148
	v_and_b32_e32 v19, 0xffff0000, v148
	v_lshlrev_b32_e32 v20, 16, v149
	v_and_b32_e32 v21, 0xffff0000, v149
	s_waitcnt lgkmcnt(8)
	v_pk_fma_f32 v[0:1], v[0:1], v[12:13], v[14:15] op_sel_hi:[1,0,1]
	v_pk_fma_f32 v[2:3], v[2:3], v[12:13], v[16:17] op_sel_hi:[1,0,1]
	v_pk_fma_f32 v[4:5], v[4:5], v[12:13], v[18:19] op_sel_hi:[1,0,1]
	v_pk_fma_f32 v[6:7], v[6:7], v[12:13], v[20:21] op_sel_hi:[1,0,1]
	s_waitcnt lgkmcnt(7)
	v_mfma_f32_16x16x32_bf16 v[0:3], v[130:133], v[24:27], v[0:3]
	s_waitcnt lgkmcnt(6)
	v_mfma_f32_16x16x32_bf16 v[4:7], v[130:133], v[28:31], v[4:7]
	s_waitcnt lgkmcnt(5)
	v_mfma_f32_16x16x32_bf16 v[0:3], v[134:137], v[32:35], v[0:3]
	s_waitcnt lgkmcnt(4)
	v_mfma_f32_16x16x32_bf16 v[4:7], v[134:137], v[36:39], v[4:7]
	s_waitcnt lgkmcnt(3)
	v_mfma_f32_16x16x32_bf16 v[0:3], v[138:141], v[40:43], v[0:3]
	s_waitcnt lgkmcnt(2)
	v_mfma_f32_16x16x32_bf16 v[4:7], v[138:141], v[44:47], v[4:7]
	s_waitcnt lgkmcnt(1)
	v_mfma_f32_16x16x32_bf16 v[0:3], v[142:145], v[48:51], v[0:3]
	s_waitcnt lgkmcnt(0)
	v_mfma_f32_16x16x32_bf16 v[4:7], v[142:145], v[52:55], v[4:7]
	s_add_u32 s7, s6, 15
	s_min_u32 s7, s7, 0x80
	s_mul_i32 s7, s7, 0x60000
	s_add_u32 s10, s2, s7
	s_addc_u32 s11, s3, 0
	global_load_dwordx4 v[130:133], v56, s[10:11] offset:0
	global_load_dwordx4 v[134:137], v56, s[10:11] offset:1024
	global_load_dwordx4 v[138:141], v56, s[10:11] offset:2048
	global_load_dwordx4 v[142:145], v56, s[10:11] offset:3072
	global_load_dwordx2 v[146:147], v57, s[10:11]
	global_load_dwordx2 v[148:149], v57, s[10:11] offset:512
	v_cvt_pk_bf16_f32 v8, v0, v1
	v_cvt_pk_bf16_f32 v9, v2, v3
	v_cvt_pk_bf16_f32 v10, v4, v5
	v_cvt_pk_bf16_f32 v11, v6, v7
	ds_write_b64 v64, v[8:9] offset:0
	ds_write_b64 v64, v[10:11] offset:4096
	s_mov_b32 s6, 8
	v_add_u32_e32 v65, 32, v65
.Ldnch_loop_l0:
	s_waitcnt lgkmcnt(0)
	s_barrier
	global_store_dwordx2 v58, v[8:9], s[4:5]
	global_store_dwordx2 v59, v[10:11], s[4:5]
	ds_read_b32 v12, v65 offset:16384
	ds_read_b128 v[24:27], v60 offset:0
	ds_read_b128 v[28:31], v60 offset:4096
	ds_read_b128 v[32:35], v61 offset:0
	ds_read_b128 v[36:39], v61 offset:4096
	ds_read_b128 v[40:43], v62 offset:0
	ds_read_b128 v[44:47], v62 offset:4096
	ds_read_b128 v[48:51], v63 offset:0
	ds_read_b128 v[52:55], v63 offset:4096
	s_add_u32 s4, s4, 0x20000
	s_addc_u32 s5, s5, 0
	s_waitcnt vmcnt(58)
	v_lshlrev_b32_e32 v14, 16, v170
	v_and_b32_e32 v15, 0xffff0000, v170
	v_lshlrev_b32_e32 v16, 16, v171
	v_and_b32_e32 v17, 0xffff0000, v171
	v_lshlrev_b32_e32 v18, 16, v172
	v_and_b32_e32 v19, 0xffff0000, v172
	v_lshlrev_b32_e32 v20, 16, v173
	v_and_b32_e32 v21, 0xffff0000, v173
	s_waitcnt lgkmcnt(8)
	v_pk_fma_f32 v[0:1], v[0:1], v[12:13], v[14:15] op_sel_hi:[1,0,1]
	v_pk_fma_f32 v[2:3], v[2:3], v[12:13], v[16:17] op_sel_hi:[1,0,1]
	v_pk_fma_f32 v[4:5], v[4:5], v[12:13], v[18:19] op_sel_hi:[1,0,1]
	v_pk_fma_f32 v[6:7], v[6:7], v[12:13], v[20:21] op_sel_hi:[1,0,1]
	s_waitcnt lgkmcnt(7)
	v_mfma_f32_16x16x32_bf16 v[0:3], v[154:157], v[24:27], v[0:3]
	s_waitcnt lgkmcnt(6)
	v_mfma_f32_16x16x32_bf16 v[4:7], v[154:157], v[28:31], v[4:7]
	s_waitcnt lgkmcnt(5)
	v_mfma_f32_16x16x32_bf16 v[0:3], v[158:161], v[32:35], v[0:3]
	s_waitcnt lgkmcnt(4)
	v_mfma_f32_16x16x32_bf16 v[4:7], v[158:161], v[36:39], v[4:7]
	s_waitcnt lgkmcnt(3)
	v_mfma_f32_16x16x32_bf16 v[0:3], v[162:165], v[40:43], v[0:3]
	s_waitcnt lgkmcnt(2)
	v_mfma_f32_16x16x32_bf16 v[4:7], v[162:165], v[44:47], v[4:7]
	s_waitcnt lgkmcnt(1)
	v_mfma_f32_16x16x32_bf16 v[0:3], v[166:169], v[48:51], v[0:3]
	s_waitcnt lgkmcnt(0)
	v_mfma_f32_16x16x32_bf16 v[4:7], v[166:169], v[52:55], v[4:7]
	s_add_u32 s7, s6, 8
	s_min_u32 s7, s7, 0x80
	s_mul_i32 s7, s7, 0x60000
	s_add_u32 s10, s2, s7
	s_addc_u32 s11, s3, 0
	global_load_dwordx4 v[154:157], v56, s[10:11] offset:0
	global_load_dwordx4 v[158:161], v56, s[10:11] offset:1024
	global_load_dwordx4 v[162:165], v56, s[10:11] offset:2048
	global_load_dwordx4 v[166:169], v56, s[10:11] offset:3072
	global_load_dwordx2 v[170:171], v57, s[10:11]
	global_load_dwordx2 v[172:173], v57, s[10:11] offset:512
	v_cvt_pk_bf16_f32 v8, v0, v1
	v_cvt_pk_bf16_f32 v9, v2, v3
	v_cvt_pk_bf16_f32 v10, v4, v5
	v_cvt_pk_bf16_f32 v11, v6, v7
	ds_write_b64 v64, v[8:9] offset:8192
	ds_write_b64 v64, v[10:11] offset:12288
	s_waitcnt lgkmcnt(0)
	s_barrier
	global_store_dwordx2 v58, v[8:9], s[4:5]
	global_store_dwordx2 v59, v[10:11], s[4:5]
	ds_read_b32 v12, v65 offset:16388
	ds_read_b128 v[24:27], v60 offset:8192
	ds_read_b128 v[28:31], v60 offset:12288
	ds_read_b128 v[32:35], v61 offset:8192
	ds_read_b128 v[36:39], v61 offset:12288
	ds_read_b128 v[40:43], v62 offset:8192
	ds_read_b128 v[44:47], v62 offset:12288
	ds_read_b128 v[48:51], v63 offset:8192
	ds_read_b128 v[52:55], v63 offset:12288
	s_add_u32 s4, s4, 0x20000
	s_addc_u32 s5, s5, 0
	s_waitcnt vmcnt(58)
	v_lshlrev_b32_e32 v14, 16, v190
	v_and_b32_e32 v15, 0xffff0000, v190
	v_lshlrev_b32_e32 v16, 16, v191
	v_and_b32_e32 v17, 0xffff0000, v191
	v_lshlrev_b32_e32 v18, 16, v192
	v_and_b32_e32 v19, 0xffff0000, v192
	v_lshlrev_b32_e32 v20, 16, v193
	v_and_b32_e32 v21, 0xffff0000, v193
	s_waitcnt lgkmcnt(8)
	v_pk_fma_f32 v[0:1], v[0:1], v[12:13], v[14:15] op_sel_hi:[1,0,1]
	v_pk_fma_f32 v[2:3], v[2:3], v[12:13], v[16:17] op_sel_hi:[1,0,1]
	v_pk_fma_f32 v[4:5], v[4:5], v[12:13], v[18:19] op_sel_hi:[1,0,1]
	v_pk_fma_f32 v[6:7], v[6:7], v[12:13], v[20:21] op_sel_hi:[1,0,1]
	s_waitcnt lgkmcnt(7)
	v_mfma_f32_16x16x32_bf16 v[0:3], v[174:177], v[24:27], v[0:3]
	s_waitcnt lgkmcnt(6)
	v_mfma_f32_16x16x32_bf16 v[4:7], v[174:177], v[28:31], v[4:7]
	s_waitcnt lgkmcnt(5)
	v_mfma_f32_16x16x32_bf16 v[0:3], v[178:181], v[32:35], v[0:3]
	s_waitcnt lgkmcnt(4)
	v_mfma_f32_16x16x32_bf16 v[4:7], v[178:181], v[36:39], v[4:7]
	s_waitcnt lgkmcnt(3)
	v_mfma_f32_16x16x32_bf16 v[0:3], v[182:185], v[40:43], v[0:3]
	s_waitcnt lgkmcnt(2)
	v_mfma_f32_16x16x32_bf16 v[4:7], v[182:185], v[44:47], v[4:7]
	s_waitcnt lgkmcnt(1)
	v_mfma_f32_16x16x32_bf16 v[0:3], v[186:189], v[48:51], v[0:3]
	s_waitcnt lgkmcnt(0)
	v_mfma_f32_16x16x32_bf16 v[4:7], v[186:189], v[52:55], v[4:7]
	s_add_u32 s7, s6, 9
	s_min_u32 s7, s7, 0x80
	s_mul_i32 s7, s7, 0x60000
	s_add_u32 s10, s2, s7
	s_addc_u32 s11, s3, 0
	global_load_dwordx4 v[174:177], v56, s[10:11] offset:0
	global_load_dwordx4 v[178:181], v56, s[10:11] offset:1024
	global_load_dwordx4 v[182:185], v56, s[10:11] offset:2048
	global_load_dwordx4 v[186:189], v56, s[10:11] offset:3072
	global_load_dwordx2 v[190:191], v57, s[10:11]
	global_load_dwordx2 v[192:193], v57, s[10:11] offset:512
	v_cvt_pk_bf16_f32 v8, v0, v1
	v_cvt_pk_bf16_f32 v9, v2, v3
	v_cvt_pk_bf16_f32 v10, v4, v5
	v_cvt_pk_bf16_f32 v11, v6, v7
	ds_write_b64 v64, v[8:9] offset:0
	ds_write_b64 v64, v[10:11] offset:4096
	s_waitcnt lgkmcnt(0)
	s_barrier
	global_store_dwordx2 v58, v[8:9], s[4:5]
	global_store_dwordx2 v59, v[10:11], s[4:5]
	ds_read_b32 v12, v65 offset:16392
	ds_read_b128 v[24:27], v60 offset:0
	ds_read_b128 v[28:31], v60 offset:4096
	ds_read_b128 v[32:35], v61 offset:0
	ds_read_b128 v[36:39], v61 offset:4096
	ds_read_b128 v[40:43], v62 offset:0
	ds_read_b128 v[44:47], v62 offset:4096
	ds_read_b128 v[48:51], v63 offset:0
	ds_read_b128 v[52:55], v63 offset:4096
	s_add_u32 s4, s4, 0x20000
	s_addc_u32 s5, s5, 0
	s_waitcnt vmcnt(58)
	v_lshlrev_b32_e32 v14, 16, v210
	v_and_b32_e32 v15, 0xffff0000, v210
	v_lshlrev_b32_e32 v16, 16, v211
	v_and_b32_e32 v17, 0xffff0000, v211
	v_lshlrev_b32_e32 v18, 16, v212
	v_and_b32_e32 v19, 0xffff0000, v212
	v_lshlrev_b32_e32 v20, 16, v213
	v_and_b32_e32 v21, 0xffff0000, v213
	s_waitcnt lgkmcnt(8)
	v_pk_fma_f32 v[0:1], v[0:1], v[12:13], v[14:15] op_sel_hi:[1,0,1]
	v_pk_fma_f32 v[2:3], v[2:3], v[12:13], v[16:17] op_sel_hi:[1,0,1]
	v_pk_fma_f32 v[4:5], v[4:5], v[12:13], v[18:19] op_sel_hi:[1,0,1]
	v_pk_fma_f32 v[6:7], v[6:7], v[12:13], v[20:21] op_sel_hi:[1,0,1]
	s_waitcnt lgkmcnt(7)
	v_mfma_f32_16x16x32_bf16 v[0:3], v[194:197], v[24:27], v[0:3]
	s_waitcnt lgkmcnt(6)
	v_mfma_f32_16x16x32_bf16 v[4:7], v[194:197], v[28:31], v[4:7]
	s_waitcnt lgkmcnt(5)
	v_mfma_f32_16x16x32_bf16 v[0:3], v[198:201], v[32:35], v[0:3]
	s_waitcnt lgkmcnt(4)
	v_mfma_f32_16x16x32_bf16 v[4:7], v[198:201], v[36:39], v[4:7]
	s_waitcnt lgkmcnt(3)
	v_mfma_f32_16x16x32_bf16 v[0:3], v[202:205], v[40:43], v[0:3]
	s_waitcnt lgkmcnt(2)
	v_mfma_f32_16x16x32_bf16 v[4:7], v[202:205], v[44:47], v[4:7]
	s_waitcnt lgkmcnt(1)
	v_mfma_f32_16x16x32_bf16 v[0:3], v[206:209], v[48:51], v[0:3]
	s_waitcnt lgkmcnt(0)
	v_mfma_f32_16x16x32_bf16 v[4:7], v[206:209], v[52:55], v[4:7]
	s_add_u32 s7, s6, 10
	s_min_u32 s7, s7, 0x80
	s_mul_i32 s7, s7, 0x60000
	s_add_u32 s10, s2, s7
	s_addc_u32 s11, s3, 0
	global_load_dwordx4 v[194:197], v56, s[10:11] offset:0
	global_load_dwordx4 v[198:201], v56, s[10:11] offset:1024
	global_load_dwordx4 v[202:205], v56, s[10:11] offset:2048
	global_load_dwordx4 v[206:209], v56, s[10:11] offset:3072
	global_load_dwordx2 v[210:211], v57, s[10:11]
	global_load_dwordx2 v[212:213], v57, s[10:11] offset:512
	v_cvt_pk_bf16_f32 v8, v0, v1
	v_cvt_pk_bf16_f32 v9, v2, v3
	v_cvt_pk_bf16_f32 v10, v4, v5
	v_cvt_pk_bf16_f32 v11, v6, v7
	ds_write_b64 v64, v[8:9] offset:8192
	ds_write_b64 v64, v[10:11] offset:12288
	s_waitcnt lgkmcnt(0)
	s_barrier
	global_store_dwordx2 v58, v[8:9], s[4:5]
	global_store_dwordx2 v59, v[10:11], s[4:5]
	ds_read_b32 v12, v65 offset:16396
	ds_read_b128 v[24:27], v60 offset:8192
	ds_read_b128 v[28:31], v60 offset:12288
	ds_read_b128 v[32:35], v61 offset:8192
	ds_read_b128 v[36:39], v61 offset:12288
	ds_read_b128 v[40:43], v62 offset:8192
	ds_read_b128 v[44:47], v62 offset:12288
	ds_read_b128 v[48:51], v63 offset:8192
	ds_read_b128 v[52:55], v63 offset:12288
	s_add_u32 s4, s4, 0x20000
	s_addc_u32 s5, s5, 0
	s_waitcnt vmcnt(58)
	v_lshlrev_b32_e32 v14, 16, v230
	v_and_b32_e32 v15, 0xffff0000, v230
	v_lshlrev_b32_e32 v16, 16, v231
	v_and_b32_e32 v17, 0xffff0000, v231
	v_lshlrev_b32_e32 v18, 16, v232
	v_and_b32_e32 v19, 0xffff0000, v232
	v_lshlrev_b32_e32 v20, 16, v233
	v_and_b32_e32 v21, 0xffff0000, v233
	s_waitcnt lgkmcnt(8)
	v_pk_fma_f32 v[0:1], v[0:1], v[12:13], v[14:15] op_sel_hi:[1,0,1]
	v_pk_fma_f32 v[2:3], v[2:3], v[12:13], v[16:17] op_sel_hi:[1,0,1]
	v_pk_fma_f32 v[4:5], v[4:5], v[12:13], v[18:19] op_sel_hi:[1,0,1]
	v_pk_fma_f32 v[6:7], v[6:7], v[12:13], v[20:21] op_sel_hi:[1,0,1]
	s_waitcnt lgkmcnt(7)
	v_mfma_f32_16x16x32_bf16 v[0:3], v[214:217], v[24:27], v[0:3]
	s_waitcnt lgkmcnt(6)
	v_mfma_f32_16x16x32_bf16 v[4:7], v[214:217], v[28:31], v[4:7]
	s_waitcnt lgkmcnt(5)
	v_mfma_f32_16x16x32_bf16 v[0:3], v[218:221], v[32:35], v[0:3]
	s_waitcnt lgkmcnt(4)
	v_mfma_f32_16x16x32_bf16 v[4:7], v[218:221], v[36:39], v[4:7]
	s_waitcnt lgkmcnt(3)
	v_mfma_f32_16x16x32_bf16 v[0:3], v[222:225], v[40:43], v[0:3]
	s_waitcnt lgkmcnt(2)
	v_mfma_f32_16x16x32_bf16 v[4:7], v[222:225], v[44:47], v[4:7]
	s_waitcnt lgkmcnt(1)
	v_mfma_f32_16x16x32_bf16 v[0:3], v[226:229], v[48:51], v[0:3]
	s_waitcnt lgkmcnt(0)
	v_mfma_f32_16x16x32_bf16 v[4:7], v[226:229], v[52:55], v[4:7]
	s_add_u32 s7, s6, 11
	s_min_u32 s7, s7, 0x80
	s_mul_i32 s7, s7, 0x60000
	s_add_u32 s10, s2, s7
	s_addc_u32 s11, s3, 0
	global_load_dwordx4 v[214:217], v56, s[10:11] offset:0
	global_load_dwordx4 v[218:221], v56, s[10:11] offset:1024
	global_load_dwordx4 v[222:225], v56, s[10:11] offset:2048
	global_load_dwordx4 v[226:229], v56, s[10:11] offset:3072
	global_load_dwordx2 v[230:231], v57, s[10:11]
	global_load_dwordx2 v[232:233], v57, s[10:11] offset:512
	v_cvt_pk_bf16_f32 v8, v0, v1
	v_cvt_pk_bf16_f32 v9, v2, v3
	v_cvt_pk_bf16_f32 v10, v4, v5
	v_cvt_pk_bf16_f32 v11, v6, v7
	ds_write_b64 v64, v[8:9] offset:0
	ds_write_b64 v64, v[10:11] offset:4096
	s_waitcnt lgkmcnt(0)
	s_barrier
	global_store_dwordx2 v58, v[8:9], s[4:5]
	global_store_dwordx2 v59, v[10:11], s[4:5]
	ds_read_b32 v12, v65 offset:16400
	ds_read_b128 v[24:27], v60 offset:0
	ds_read_b128 v[28:31], v60 offset:4096
	ds_read_b128 v[32:35], v61 offset:0
	ds_read_b128 v[36:39], v61 offset:4096
	ds_read_b128 v[40:43], v62 offset:0
	ds_read_b128 v[44:47], v62 offset:4096
	ds_read_b128 v[48:51], v63 offset:0
	ds_read_b128 v[52:55], v63 offset:4096
	s_add_u32 s4, s4, 0x20000
	s_addc_u32 s5, s5, 0
	s_waitcnt vmcnt(58)
	v_lshlrev_b32_e32 v14, 16, v250
	v_and_b32_e32 v15, 0xffff0000, v250
	v_lshlrev_b32_e32 v16, 16, v251
	v_and_b32_e32 v17, 0xffff0000, v251
	v_lshlrev_b32_e32 v18, 16, v252
	v_and_b32_e32 v19, 0xffff0000, v252
	v_lshlrev_b32_e32 v20, 16, v253
	v_and_b32_e32 v21, 0xffff0000, v253
	s_waitcnt lgkmcnt(8)
	v_pk_fma_f32 v[0:1], v[0:1], v[12:13], v[14:15] op_sel_hi:[1,0,1]
	v_pk_fma_f32 v[2:3], v[2:3], v[12:13], v[16:17] op_sel_hi:[1,0,1]
	v_pk_fma_f32 v[4:5], v[4:5], v[12:13], v[18:19] op_sel_hi:[1,0,1]
	v_pk_fma_f32 v[6:7], v[6:7], v[12:13], v[20:21] op_sel_hi:[1,0,1]
	s_waitcnt lgkmcnt(7)
	v_mfma_f32_16x16x32_bf16 v[0:3], v[234:237], v[24:27], v[0:3]
	s_waitcnt lgkmcnt(6)
	v_mfma_f32_16x16x32_bf16 v[4:7], v[234:237], v[28:31], v[4:7]
	s_waitcnt lgkmcnt(5)
	v_mfma_f32_16x16x32_bf16 v[0:3], v[238:241], v[32:35], v[0:3]
	s_waitcnt lgkmcnt(4)
	v_mfma_f32_16x16x32_bf16 v[4:7], v[238:241], v[36:39], v[4:7]
	s_waitcnt lgkmcnt(3)
	v_mfma_f32_16x16x32_bf16 v[0:3], v[242:245], v[40:43], v[0:3]
	s_waitcnt lgkmcnt(2)
	v_mfma_f32_16x16x32_bf16 v[4:7], v[242:245], v[44:47], v[4:7]
	s_waitcnt lgkmcnt(1)
	v_mfma_f32_16x16x32_bf16 v[0:3], v[246:249], v[48:51], v[0:3]
	s_waitcnt lgkmcnt(0)
	v_mfma_f32_16x16x32_bf16 v[4:7], v[246:249], v[52:55], v[4:7]
	s_add_u32 s7, s6, 12
	s_min_u32 s7, s7, 0x80
	s_mul_i32 s7, s7, 0x60000
	s_add_u32 s10, s2, s7
	s_addc_u32 s11, s3, 0
	global_load_dwordx4 v[234:237], v56, s[10:11] offset:0
	global_load_dwordx4 v[238:241], v56, s[10:11] offset:1024
	global_load_dwordx4 v[242:245], v56, s[10:11] offset:2048
	global_load_dwordx4 v[246:249], v56, s[10:11] offset:3072
	global_load_dwordx2 v[250:251], v57, s[10:11]
	global_load_dwordx2 v[252:253], v57, s[10:11] offset:512
	v_cvt_pk_bf16_f32 v8, v0, v1
	v_cvt_pk_bf16_f32 v9, v2, v3
	v_cvt_pk_bf16_f32 v10, v4, v5
	v_cvt_pk_bf16_f32 v11, v6, v7
	ds_write_b64 v64, v[8:9] offset:8192
	ds_write_b64 v64, v[10:11] offset:12288
	s_waitcnt lgkmcnt(0)
	s_barrier
	global_store_dwordx2 v58, v[8:9], s[4:5]
	global_store_dwordx2 v59, v[10:11], s[4:5]
	ds_read_b32 v12, v65 offset:16404
	ds_read_b128 v[24:27], v60 offset:8192
	ds_read_b128 v[28:31], v60 offset:12288
	ds_read_b128 v[32:35], v61 offset:8192
	ds_read_b128 v[36:39], v61 offset:12288
	ds_read_b128 v[40:43], v62 offset:8192
	ds_read_b128 v[44:47], v62 offset:12288
	ds_read_b128 v[48:51], v63 offset:8192
	ds_read_b128 v[52:55], v63 offset:12288
	s_add_u32 s4, s4, 0x20000
	s_addc_u32 s5, s5, 0
	s_waitcnt vmcnt(58)
	v_lshlrev_b32_e32 v14, 16, v106
	v_and_b32_e32 v15, 0xffff0000, v106
	v_lshlrev_b32_e32 v16, 16, v107
	v_and_b32_e32 v17, 0xffff0000, v107
	v_lshlrev_b32_e32 v18, 16, v108
	v_and_b32_e32 v19, 0xffff0000, v108
	v_lshlrev_b32_e32 v20, 16, v109
	v_and_b32_e32 v21, 0xffff0000, v109
	s_waitcnt lgkmcnt(8)
	v_pk_fma_f32 v[0:1], v[0:1], v[12:13], v[14:15] op_sel_hi:[1,0,1]
	v_pk_fma_f32 v[2:3], v[2:3], v[12:13], v[16:17] op_sel_hi:[1,0,1]
	v_pk_fma_f32 v[4:5], v[4:5], v[12:13], v[18:19] op_sel_hi:[1,0,1]
	v_pk_fma_f32 v[6:7], v[6:7], v[12:13], v[20:21] op_sel_hi:[1,0,1]
	s_waitcnt lgkmcnt(7)
	v_mfma_f32_16x16x32_bf16 v[0:3], v[90:93], v[24:27], v[0:3]
	s_waitcnt lgkmcnt(6)
	v_mfma_f32_16x16x32_bf16 v[4:7], v[90:93], v[28:31], v[4:7]
	s_waitcnt lgkmcnt(5)
	v_mfma_f32_16x16x32_bf16 v[0:3], v[94:97], v[32:35], v[0:3]
	s_waitcnt lgkmcnt(4)
	v_mfma_f32_16x16x32_bf16 v[4:7], v[94:97], v[36:39], v[4:7]
	s_waitcnt lgkmcnt(3)
	v_mfma_f32_16x16x32_bf16 v[0:3], v[98:101], v[40:43], v[0:3]
	s_waitcnt lgkmcnt(2)
	v_mfma_f32_16x16x32_bf16 v[4:7], v[98:101], v[44:47], v[4:7]
	s_waitcnt lgkmcnt(1)
	v_mfma_f32_16x16x32_bf16 v[0:3], v[102:105], v[48:51], v[0:3]
	s_waitcnt lgkmcnt(0)
	v_mfma_f32_16x16x32_bf16 v[4:7], v[102:105], v[52:55], v[4:7]
	s_add_u32 s7, s6, 13
	s_min_u32 s7, s7, 0x80
	s_mul_i32 s7, s7, 0x60000
	s_add_u32 s10, s2, s7
	s_addc_u32 s11, s3, 0
	global_load_dwordx4 v[90:93], v56, s[10:11] offset:0
	global_load_dwordx4 v[94:97], v56, s[10:11] offset:1024
	global_load_dwordx4 v[98:101], v56, s[10:11] offset:2048
	global_load_dwordx4 v[102:105], v56, s[10:11] offset:3072
	global_load_dwordx2 v[106:107], v57, s[10:11]
	global_load_dwordx2 v[108:109], v57, s[10:11] offset:512
	v_cvt_pk_bf16_f32 v8, v0, v1
	v_cvt_pk_bf16_f32 v9, v2, v3
	v_cvt_pk_bf16_f32 v10, v4, v5
	v_cvt_pk_bf16_f32 v11, v6, v7
	ds_write_b64 v64, v[8:9] offset:0
	ds_write_b64 v64, v[10:11] offset:4096
	s_waitcnt lgkmcnt(0)
	s_barrier
	global_store_dwordx2 v58, v[8:9], s[4:5]
	global_store_dwordx2 v59, v[10:11], s[4:5]
	ds_read_b32 v12, v65 offset:16408
	ds_read_b128 v[24:27], v60 offset:0
	ds_read_b128 v[28:31], v60 offset:4096
	ds_read_b128 v[32:35], v61 offset:0
	ds_read_b128 v[36:39], v61 offset:4096
	ds_read_b128 v[40:43], v62 offset:0
	ds_read_b128 v[44:47], v62 offset:4096
	ds_read_b128 v[48:51], v63 offset:0
	ds_read_b128 v[52:55], v63 offset:4096
	s_add_u32 s4, s4, 0x20000
	s_addc_u32 s5, s5, 0
	s_waitcnt vmcnt(58)
	v_lshlrev_b32_e32 v14, 16, v126
	v_and_b32_e32 v15, 0xffff0000, v126
	v_lshlrev_b32_e32 v16, 16, v127
	v_and_b32_e32 v17, 0xffff0000, v127
	v_lshlrev_b32_e32 v18, 16, v128
	v_and_b32_e32 v19, 0xffff0000, v128
	v_lshlrev_b32_e32 v20, 16, v129
	v_and_b32_e32 v21, 0xffff0000, v129
	s_waitcnt lgkmcnt(8)
	v_pk_fma_f32 v[0:1], v[0:1], v[12:13], v[14:15] op_sel_hi:[1,0,1]
	v_pk_fma_f32 v[2:3], v[2:3], v[12:13], v[16:17] op_sel_hi:[1,0,1]
	v_pk_fma_f32 v[4:5], v[4:5], v[12:13], v[18:19] op_sel_hi:[1,0,1]
	v_pk_fma_f32 v[6:7], v[6:7], v[12:13], v[20:21] op_sel_hi:[1,0,1]
	s_waitcnt lgkmcnt(7)
	v_mfma_f32_16x16x32_bf16 v[0:3], v[110:113], v[24:27], v[0:3]
	s_waitcnt lgkmcnt(6)
	v_mfma_f32_16x16x32_bf16 v[4:7], v[110:113], v[28:31], v[4:7]
	s_waitcnt lgkmcnt(5)
	v_mfma_f32_16x16x32_bf16 v[0:3], v[114:117], v[32:35], v[0:3]
	s_waitcnt lgkmcnt(4)
	v_mfma_f32_16x16x32_bf16 v[4:7], v[114:117], v[36:39], v[4:7]
	s_waitcnt lgkmcnt(3)
	v_mfma_f32_16x16x32_bf16 v[0:3], v[118:121], v[40:43], v[0:3]
	s_waitcnt lgkmcnt(2)
	v_mfma_f32_16x16x32_bf16 v[4:7], v[118:121], v[44:47], v[4:7]
	s_waitcnt lgkmcnt(1)
	v_mfma_f32_16x16x32_bf16 v[0:3], v[122:125], v[48:51], v[0:3]
	s_waitcnt lgkmcnt(0)
	v_mfma_f32_16x16x32_bf16 v[4:7], v[122:125], v[52:55], v[4:7]
	s_add_u32 s7, s6, 14
	s_min_u32 s7, s7, 0x80
	s_mul_i32 s7, s7, 0x60000
	s_add_u32 s10, s2, s7
	s_addc_u32 s11, s3, 0
	global_load_dwordx4 v[110:113], v56, s[10:11] offset:0
	global_load_dwordx4 v[114:117], v56, s[10:11] offset:1024
	global_load_dwordx4 v[118:121], v56, s[10:11] offset:2048
	global_load_dwordx4 v[122:125], v56, s[10:11] offset:3072
	global_load_dwordx2 v[126:127], v57, s[10:11]
	global_load_dwordx2 v[128:129], v57, s[10:11] offset:512
	v_cvt_pk_bf16_f32 v8, v0, v1
	v_cvt_pk_bf16_f32 v9, v2, v3
	v_cvt_pk_bf16_f32 v10, v4, v5
	v_cvt_pk_bf16_f32 v11, v6, v7
	ds_write_b64 v64, v[8:9] offset:8192
	ds_write_b64 v64, v[10:11] offset:12288
	s_waitcnt lgkmcnt(0)
	s_barrier
	global_store_dwordx2 v58, v[8:9], s[4:5]
	global_store_dwordx2 v59, v[10:11], s[4:5]
	ds_read_b32 v12, v65 offset:16412
	ds_read_b128 v[24:27], v60 offset:8192
	ds_read_b128 v[28:31], v60 offset:12288
	ds_read_b128 v[32:35], v61 offset:8192
	ds_read_b128 v[36:39], v61 offset:12288
	ds_read_b128 v[40:43], v62 offset:8192
	ds_read_b128 v[44:47], v62 offset:12288
	ds_read_b128 v[48:51], v63 offset:8192
	ds_read_b128 v[52:55], v63 offset:12288
	s_add_u32 s4, s4, 0x20000
	s_addc_u32 s5, s5, 0
	s_waitcnt vmcnt(58)
	v_lshlrev_b32_e32 v14, 16, v146
	v_and_b32_e32 v15, 0xffff0000, v146
	v_lshlrev_b32_e32 v16, 16, v147
	v_and_b32_e32 v17, 0xffff0000, v147
	v_lshlrev_b32_e32 v18, 16, v148
	v_and_b32_e32 v19, 0xffff0000, v148
	v_lshlrev_b32_e32 v20, 16, v149
	v_and_b32_e32 v21, 0xffff0000, v149
	s_waitcnt lgkmcnt(8)
	v_pk_fma_f32 v[0:1], v[0:1], v[12:13], v[14:15] op_sel_hi:[1,0,1]
	v_pk_fma_f32 v[2:3], v[2:3], v[12:13], v[16:17] op_sel_hi:[1,0,1]
	v_pk_fma_f32 v[4:5], v[4:5], v[12:13], v[18:19] op_sel_hi:[1,0,1]
	v_pk_fma_f32 v[6:7], v[6:7], v[12:13], v[20:21] op_sel_hi:[1,0,1]
	s_waitcnt lgkmcnt(7)
	v_mfma_f32_16x16x32_bf16 v[0:3], v[130:133], v[24:27], v[0:3]
	s_waitcnt lgkmcnt(6)
	v_mfma_f32_16x16x32_bf16 v[4:7], v[130:133], v[28:31], v[4:7]
	s_waitcnt lgkmcnt(5)
	v_mfma_f32_16x16x32_bf16 v[0:3], v[134:137], v[32:35], v[0:3]
	s_waitcnt lgkmcnt(4)
	v_mfma_f32_16x16x32_bf16 v[4:7], v[134:137], v[36:39], v[4:7]
	s_waitcnt lgkmcnt(3)
	v_mfma_f32_16x16x32_bf16 v[0:3], v[138:141], v[40:43], v[0:3]
	s_waitcnt lgkmcnt(2)
	v_mfma_f32_16x16x32_bf16 v[4:7], v[138:141], v[44:47], v[4:7]
	s_waitcnt lgkmcnt(1)
	v_mfma_f32_16x16x32_bf16 v[0:3], v[142:145], v[48:51], v[0:3]
	s_waitcnt lgkmcnt(0)
	v_mfma_f32_16x16x32_bf16 v[4:7], v[142:145], v[52:55], v[4:7]
	s_add_u32 s7, s6, 15
	s_min_u32 s7, s7, 0x80
	s_mul_i32 s7, s7, 0x60000
	s_add_u32 s10, s2, s7
	s_addc_u32 s11, s3, 0
	global_load_dwordx4 v[130:133], v56, s[10:11] offset:0
	global_load_dwordx4 v[134:137], v56, s[10:11] offset:1024
	global_load_dwordx4 v[138:141], v56, s[10:11] offset:2048
	global_load_dwordx4 v[142:145], v56, s[10:11] offset:3072
	global_load_dwordx2 v[146:147], v57, s[10:11]
	global_load_dwordx2 v[148:149], v57, s[10:11] offset:512
	v_cvt_pk_bf16_f32 v8, v0, v1
	v_cvt_pk_bf16_f32 v9, v2, v3
	v_cvt_pk_bf16_f32 v10, v4, v5
	v_cvt_pk_bf16_f32 v11, v6, v7
	ds_write_b64 v64, v[8:9] offset:0
	ds_write_b64 v64, v[10:11] offset:4096
	s_add_u32 s6, s6, 8
	v_add_u32_e32 v65, 32, v65
	s_cmp_lt_u32 s6, 128
	s_cbranch_scc1 .Ldnch_loop_l0
	s_waitcnt lgkmcnt(0)
	s_barrier
	global_store_dwordx2 v58, v[8:9], s[4:5]
	global_store_dwordx2 v59, v[10:11], s[4:5]
	ds_read_b32 v12, v65 offset:16384
	ds_read_b128 v[24:27], v60 offset:0
	ds_read_b128 v[28:31], v60 offset:4096
	ds_read_b128 v[32:35], v61 offset:0
	ds_read_b128 v[36:39], v61 offset:4096
	ds_read_b128 v[40:43], v62 offset:0
	ds_read_b128 v[44:47], v62 offset:4096
	ds_read_b128 v[48:51], v63 offset:0
	ds_read_b128 v[52:55], v63 offset:4096
	s_add_u32 s4, s4, 0x20000
	s_addc_u32 s5, s5, 0
	s_waitcnt vmcnt(58)
	v_lshlrev_b32_e32 v14, 16, v170
	v_and_b32_e32 v15, 0xffff0000, v170
	v_lshlrev_b32_e32 v16, 16, v171
	v_and_b32_e32 v17, 0xffff0000, v171
	v_lshlrev_b32_e32 v18, 16, v172
	v_and_b32_e32 v19, 0xffff0000, v172
	v_lshlrev_b32_e32 v20, 16, v173
	v_and_b32_e32 v21, 0xffff0000, v173
	s_waitcnt lgkmcnt(8)
	v_pk_fma_f32 v[0:1], v[0:1], v[12:13], v[14:15] op_sel_hi:[1,0,1]
	v_pk_fma_f32 v[2:3], v[2:3], v[12:13], v[16:17] op_sel_hi:[1,0,1]
	v_pk_fma_f32 v[4:5], v[4:5], v[12:13], v[18:19] op_sel_hi:[1,0,1]
	v_pk_fma_f32 v[6:7], v[6:7], v[12:13], v[20:21] op_sel_hi:[1,0,1]
	s_waitcnt lgkmcnt(7)
	v_mfma_f32_16x16x32_bf16 v[0:3], v[154:157], v[24:27], v[0:3]
	s_waitcnt lgkmcnt(6)
	v_mfma_f32_16x16x32_bf16 v[4:7], v[154:157], v[28:31], v[4:7]
	s_waitcnt lgkmcnt(5)
	v_mfma_f32_16x16x32_bf16 v[0:3], v[158:161], v[32:35], v[0:3]
	s_waitcnt lgkmcnt(4)
	v_mfma_f32_16x16x32_bf16 v[4:7], v[158:161], v[36:39], v[4:7]
	s_waitcnt lgkmcnt(3)
	v_mfma_f32_16x16x32_bf16 v[0:3], v[162:165], v[40:43], v[0:3]
	s_waitcnt lgkmcnt(2)
	v_mfma_f32_16x16x32_bf16 v[4:7], v[162:165], v[44:47], v[4:7]
	s_waitcnt lgkmcnt(1)
	v_mfma_f32_16x16x32_bf16 v[0:3], v[166:169], v[48:51], v[0:3]
	s_waitcnt lgkmcnt(0)
	v_mfma_f32_16x16x32_bf16 v[4:7], v[166:169], v[52:55], v[4:7]
	s_nop 7
	s_nop 1
	v_cvt_pk_bf16_f32 v8, v0, v1
	v_cvt_pk_bf16_f32 v9, v2, v3
	v_cvt_pk_bf16_f32 v10, v4, v5
	v_cvt_pk_bf16_f32 v11, v6, v7
	ds_write_b64 v64, v[8:9] offset:8192
	ds_write_b64 v64, v[10:11] offset:12288
	s_lshl_b32 s14, s13, 16
	s_add_u32 s16, s20, s14
	s_addc_u32 s17, s21, 0
	s_add_u32 s16, s16, 0x4400000
	s_addc_u32 s17, s17, 0
	v_and_b32_e32 v68, 15, v66
	v_lshrrev_b32_e32 v69, 4, v66
	v_lshlrev_b32_e32 v70, 2, v69
	s_lshl_b32 s14, s0, 4
	v_add_u32_e32 v70, s14, v70
	v_lshlrev_b32_e32 v70, 7, v70
	s_and_b32 s14, s1, 31
	s_lshl_b32 s14, s14, 5
	v_add3_u32 v70, v70, s14, v68
	v_lshlrev_b32_e32 v70, 2, v70
	global_store_dword v70, v0, s[16:17] offset:0
	global_store_dword v70, v1, s[16:17] offset:512
	global_store_dword v70, v2, s[16:17] offset:1024
	global_store_dword v70, v3, s[16:17] offset:1536
	global_store_dword v70, v4, s[16:17] offset:64
	global_store_dword v70, v5, s[16:17] offset:576
	global_store_dword v70, v6, s[16:17] offset:1088
	global_store_dword v70, v7, s[16:17] offset:1600
	s_waitcnt vmcnt(0) lgkmcnt(0)
	s_barrier
	s_branch .LBB0_569

.Ldnch_loop_l1:
	s_waitcnt lgkmcnt(0)
	s_barrier
	global_store_dwordx2 v58, v[8:9], s[4:5]
	global_store_dwordx2 v59, v[10:11], s[4:5]
	ds_read_b32 v12, v65 offset:16384
	ds_read_b128 v[24:27], v60 offset:0
	ds_read_b128 v[28:31], v60 offset:4096
	ds_read_b128 v[32:35], v61 offset:0
	ds_read_b128 v[36:39], v61 offset:4096
	ds_read_b128 v[40:43], v62 offset:0
	ds_read_b128 v[44:47], v62 offset:4096
	ds_read_b128 v[48:51], v63 offset:0
	ds_read_b128 v[52:55], v63 offset:4096
	s_add_u32 s4, s4, 0x20000
	s_addc_u32 s5, s5, 0
	s_waitcnt vmcnt(58)
	v_lshlrev_b32_e32 v14, 16, v170
	v_and_b32_e32 v15, 0xffff0000, v170
	v_lshlrev_b32_e32 v16, 16, v171
	v_and_b32_e32 v17, 0xffff0000, v171
	v_lshlrev_b32_e32 v18, 16, v172
	v_and_b32_e32 v19, 0xffff0000, v172
	v_lshlrev_b32_e32 v20, 16, v173
	v_and_b32_e32 v21, 0xffff0000, v173
	s_waitcnt lgkmcnt(8)
	v_pk_fma_f32 v[0:1], v[0:1], v[12:13], v[14:15] op_sel_hi:[1,0,1]
	v_pk_fma_f32 v[2:3], v[2:3], v[12:13], v[16:17] op_sel_hi:[1,0,1]
	v_pk_fma_f32 v[4:5], v[4:5], v[12:13], v[18:19] op_sel_hi:[1,0,1]
	v_pk_fma_f32 v[6:7], v[6:7], v[12:13], v[20:21] op_sel_hi:[1,0,1]
	s_waitcnt lgkmcnt(7)
	v_mfma_f32_16x16x32_bf16 v[0:3], v[154:157], v[24:27], v[0:3]
	s_waitcnt lgkmcnt(6)
	v_mfma_f32_16x16x32_bf16 v[4:7], v[154:157], v[28:31], v[4:7]
	s_waitcnt lgkmcnt(5)
	v_mfma_f32_16x16x32_bf16 v[0:3], v[158:161], v[32:35], v[0:3]
	s_waitcnt lgkmcnt(4)
	v_mfma_f32_16x16x32_bf16 v[4:7], v[158:161], v[36:39], v[4:7]
	s_waitcnt lgkmcnt(3)
	v_mfma_f32_16x16x32_bf16 v[0:3], v[162:165], v[40:43], v[0:3]
	s_waitcnt lgkmcnt(2)
	v_mfma_f32_16x16x32_bf16 v[4:7], v[162:165], v[44:47], v[4:7]
	s_waitcnt lgkmcnt(1)
	v_mfma_f32_16x16x32_bf16 v[0:3], v[166:169], v[48:51], v[0:3]
	s_waitcnt lgkmcnt(0)
	v_mfma_f32_16x16x32_bf16 v[4:7], v[166:169], v[52:55], v[4:7]
	s_add_u32 s7, s6, 8
	s_min_u32 s7, s7, 0x80
	s_mul_i32 s7, s7, 0x60000
	s_add_u32 s10, s2, s7
	s_addc_u32 s11, s3, 0
	global_load_dwordx4 v[154:157], v56, s[10:11] offset:0
	global_load_dwordx4 v[158:161], v56, s[10:11] offset:1024
	global_load_dwordx4 v[162:165], v56, s[10:11] offset:2048
	global_load_dwordx4 v[166:169], v56, s[10:11] offset:3072
	global_load_dwordx2 v[170:171], v57, s[10:11]
	global_load_dwordx2 v[172:173], v57, s[10:11] offset:512
	v_cvt_pk_bf16_f32 v8, v0, v1
	v_cvt_pk_bf16_f32 v9, v2, v3
	v_cvt_pk_bf16_f32 v10, v4, v5
	v_cvt_pk_bf16_f32 v11, v6, v7
	ds_write_b64 v64, v[8:9] offset:8192
	ds_write_b64 v64, v[10:11] offset:12288
	s_waitcnt lgkmcnt(0)
	s_barrier
	global_store_dwordx2 v58, v[8:9], s[4:5]
	global_store_dwordx2 v59, v[10:11], s[4:5]
	ds_read_b32 v12, v65 offset:16388
	ds_read_b128 v[24:27], v60 offset:8192
	ds_read_b128 v[28:31], v60 offset:12288
	ds_read_b128 v[32:35], v61 offset:8192
	ds_read_b128 v[36:39], v61 offset:12288
	ds_read_b128 v[40:43], v62 offset:8192
	ds_read_b128 v[44:47], v62 offset:12288
	ds_read_b128 v[48:51], v63 offset:8192
	ds_read_b128 v[52:55], v63 offset:12288
	s_add_u32 s4, s4, 0x20000
	s_addc_u32 s5, s5, 0
	s_waitcnt vmcnt(58)
	v_lshlrev_b32_e32 v14, 16, v190
	v_and_b32_e32 v15, 0xffff0000, v190
	v_lshlrev_b32_e32 v16, 16, v191
	v_and_b32_e32 v17, 0xffff0000, v191
	v_lshlrev_b32_e32 v18, 16, v192
	v_and_b32_e32 v19, 0xffff0000, v192
	v_lshlrev_b32_e32 v20, 16, v193
	v_and_b32_e32 v21, 0xffff0000, v193
	s_waitcnt lgkmcnt(8)
	v_pk_fma_f32 v[0:1], v[0:1], v[12:13], v[14:15] op_sel_hi:[1,0,1]
	v_pk_fma_f32 v[2:3], v[2:3], v[12:13], v[16:17] op_sel_hi:[1,0,1]
	v_pk_fma_f32 v[4:5], v[4:5], v[12:13], v[18:19] op_sel_hi:[1,0,1]
	v_pk_fma_f32 v[6:7], v[6:7], v[12:13], v[20:21] op_sel_hi:[1,0,1]
	s_waitcnt lgkmcnt(7)
	v_mfma_f32_16x16x32_bf16 v[0:3], v[174:177], v[24:27], v[0:3]
	s_waitcnt lgkmcnt(6)
	v_mfma_f32_16x16x32_bf16 v[4:7], v[174:177], v[28:31], v[4:7]
	s_waitcnt lgkmcnt(5)
	v_mfma_f32_16x16x32_bf16 v[0:3], v[178:181], v[32:35], v[0:3]
	s_waitcnt lgkmcnt(4)
	v_mfma_f32_16x16x32_bf16 v[4:7], v[178:181], v[36:39], v[4:7]
	s_waitcnt lgkmcnt(3)
	v_mfma_f32_16x16x32_bf16 v[0:3], v[182:185], v[40:43], v[0:3]
	s_waitcnt lgkmcnt(2)
	v_mfma_f32_16x16x32_bf16 v[4:7], v[182:185], v[44:47], v[4:7]
	s_waitcnt lgkmcnt(1)
	v_mfma_f32_16x16x32_bf16 v[0:3], v[186:189], v[48:51], v[0:3]
	s_waitcnt lgkmcnt(0)
	v_mfma_f32_16x16x32_bf16 v[4:7], v[186:189], v[52:55], v[4:7]
	s_add_u32 s7, s6, 9
	s_min_u32 s7, s7, 0x80
	s_mul_i32 s7, s7, 0x60000
	s_add_u32 s10, s2, s7
	s_addc_u32 s11, s3, 0
	global_load_dwordx4 v[174:177], v56, s[10:11] offset:0
	global_load_dwordx4 v[178:181], v56, s[10:11] offset:1024
	global_load_dwordx4 v[182:185], v56, s[10:11] offset:2048
	global_load_dwordx4 v[186:189], v56, s[10:11] offset:3072
	global_load_dwordx2 v[190:191], v57, s[10:11]
	global_load_dwordx2 v[192:193], v57, s[10:11] offset:512
	v_cvt_pk_bf16_f32 v8, v0, v1
	v_cvt_pk_bf16_f32 v9, v2, v3
	v_cvt_pk_bf16_f32 v10, v4, v5
	v_cvt_pk_bf16_f32 v11, v6, v7
	ds_write_b64 v64, v[8:9] offset:0
	ds_write_b64 v64, v[10:11] offset:4096
	s_waitcnt lgkmcnt(0)
	s_barrier
	global_store_dwordx2 v58, v[8:9], s[4:5]
	global_store_dwordx2 v59, v[10:11], s[4:5]
	ds_read_b32 v12, v65 offset:16392
	ds_read_b128 v[24:27], v60 offset:0
	ds_read_b128 v[28:31], v60 offset:4096
	ds_read_b128 v[32:35], v61 offset:0
	ds_read_b128 v[36:39], v61 offset:4096
	ds_read_b128 v[40:43], v62 offset:0
	ds_read_b128 v[44:47], v62 offset:4096
	ds_read_b128 v[48:51], v63 offset:0
	ds_read_b128 v[52:55], v63 offset:4096
	s_add_u32 s4, s4, 0x20000
	s_addc_u32 s5, s5, 0
	s_waitcnt vmcnt(58)
	v_lshlrev_b32_e32 v14, 16, v210
	v_and_b32_e32 v15, 0xffff0000, v210
	v_lshlrev_b32_e32 v16, 16, v211
	v_and_b32_e32 v17, 0xffff0000, v211
	v_lshlrev_b32_e32 v18, 16, v212
	v_and_b32_e32 v19, 0xffff0000, v212
	v_lshlrev_b32_e32 v20, 16, v213
	v_and_b32_e32 v21, 0xffff0000, v213
	s_waitcnt lgkmcnt(8)
	v_pk_fma_f32 v[0:1], v[0:1], v[12:13], v[14:15] op_sel_hi:[1,0,1]
	v_pk_fma_f32 v[2:3], v[2:3], v[12:13], v[16:17] op_sel_hi:[1,0,1]
	v_pk_fma_f32 v[4:5], v[4:5], v[12:13], v[18:19] op_sel_hi:[1,0,1]
	v_pk_fma_f32 v[6:7], v[6:7], v[12:13], v[20:21] op_sel_hi:[1,0,1]
	s_waitcnt lgkmcnt(7)
	v_mfma_f32_16x16x32_bf16 v[0:3], v[194:197], v[24:27], v[0:3]
	s_waitcnt lgkmcnt(6)
	v_mfma_f32_16x16x32_bf16 v[4:7], v[194:197], v[28:31], v[4:7]
	s_waitcnt lgkmcnt(5)
	v_mfma_f32_16x16x32_bf16 v[0:3], v[198:201], v[32:35], v[0:3]
	s_waitcnt lgkmcnt(4)
	v_mfma_f32_16x16x32_bf16 v[4:7], v[198:201], v[36:39], v[4:7]
	s_waitcnt lgkmcnt(3)
	v_mfma_f32_16x16x32_bf16 v[0:3], v[202:205], v[40:43], v[0:3]
	s_waitcnt lgkmcnt(2)
	v_mfma_f32_16x16x32_bf16 v[4:7], v[202:205], v[44:47], v[4:7]
	s_waitcnt lgkmcnt(1)
	v_mfma_f32_16x16x32_bf16 v[0:3], v[206:209], v[48:51], v[0:3]
	s_waitcnt lgkmcnt(0)
	v_mfma_f32_16x16x32_bf16 v[4:7], v[206:209], v[52:55], v[4:7]
	s_add_u32 s7, s6, 10
	s_min_u32 s7, s7, 0x80
	s_mul_i32 s7, s7, 0x60000
	s_add_u32 s10, s2, s7
	s_addc_u32 s11, s3, 0
	global_load_dwordx4 v[194:197], v56, s[10:11] offset:0
	global_load_dwordx4 v[198:201], v56, s[10:11] offset:1024
	global_load_dwordx4 v[202:205], v56, s[10:11] offset:2048
	global_load_dwordx4 v[206:209], v56, s[10:11] offset:3072
	global_load_dwordx2 v[210:211], v57, s[10:11]
	global_load_dwordx2 v[212:213], v57, s[10:11] offset:512
	v_cvt_pk_bf16_f32 v8, v0, v1
	v_cvt_pk_bf16_f32 v9, v2, v3
	v_cvt_pk_bf16_f32 v10, v4, v5
	v_cvt_pk_bf16_f32 v11, v6, v7
	ds_write_b64 v64, v[8:9] offset:8192
	ds_write_b64 v64, v[10:11] offset:12288
	s_waitcnt lgkmcnt(0)
	s_barrier
	global_store_dwordx2 v58, v[8:9], s[4:5]
	global_store_dwordx2 v59, v[10:11], s[4:5]
	ds_read_b32 v12, v65 offset:16396
	ds_read_b128 v[24:27], v60 offset:8192
	ds_read_b128 v[28:31], v60 offset:12288
	ds_read_b128 v[32:35], v61 offset:8192
	ds_read_b128 v[36:39], v61 offset:12288
	ds_read_b128 v[40:43], v62 offset:8192
	ds_read_b128 v[44:47], v62 offset:12288
	ds_read_b128 v[48:51], v63 offset:8192
	ds_read_b128 v[52:55], v63 offset:12288
	s_add_u32 s4, s4, 0x20000
	s_addc_u32 s5, s5, 0
	s_waitcnt vmcnt(58)
	v_lshlrev_b32_e32 v14, 16, v230
	v_and_b32_e32 v15, 0xffff0000, v230
	v_lshlrev_b32_e32 v16, 16, v231
	v_and_b32_e32 v17, 0xffff0000, v231
	v_lshlrev_b32_e32 v18, 16, v232
	v_and_b32_e32 v19, 0xffff0000, v232
	v_lshlrev_b32_e32 v20, 16, v233
	v_and_b32_e32 v21, 0xffff0000, v233
	s_waitcnt lgkmcnt(8)
	v_pk_fma_f32 v[0:1], v[0:1], v[12:13], v[14:15] op_sel_hi:[1,0,1]
	v_pk_fma_f32 v[2:3], v[2:3], v[12:13], v[16:17] op_sel_hi:[1,0,1]
	v_pk_fma_f32 v[4:5], v[4:5], v[12:13], v[18:19] op_sel_hi:[1,0,1]
	v_pk_fma_f32 v[6:7], v[6:7], v[12:13], v[20:21] op_sel_hi:[1,0,1]
	s_waitcnt lgkmcnt(7)
	v_mfma_f32_16x16x32_bf16 v[0:3], v[214:217], v[24:27], v[0:3]
	s_waitcnt lgkmcnt(6)
	v_mfma_f32_16x16x32_bf16 v[4:7], v[214:217], v[28:31], v[4:7]
	s_waitcnt lgkmcnt(5)
	v_mfma_f32_16x16x32_bf16 v[0:3], v[218:221], v[32:35], v[0:3]
	s_waitcnt lgkmcnt(4)
	v_mfma_f32_16x16x32_bf16 v[4:7], v[218:221], v[36:39], v[4:7]
	s_waitcnt lgkmcnt(3)
	v_mfma_f32_16x16x32_bf16 v[0:3], v[222:225], v[40:43], v[0:3]
	s_waitcnt lgkmcnt(2)
	v_mfma_f32_16x16x32_bf16 v[4:7], v[222:225], v[44:47], v[4:7]
	s_waitcnt lgkmcnt(1)
	v_mfma_f32_16x16x32_bf16 v[0:3], v[226:229], v[48:51], v[0:3]
	s_waitcnt lgkmcnt(0)
	v_mfma_f32_16x16x32_bf16 v[4:7], v[226:229], v[52:55], v[4:7]
	s_add_u32 s7, s6, 11
	s_min_u32 s7, s7, 0x80
	s_mul_i32 s7, s7, 0x60000
	s_add_u32 s10, s2, s7
	s_addc_u32 s11, s3, 0
	global_load_dwordx4 v[214:217], v56, s[10:11] offset:0
	global_load_dwordx4 v[218:221], v56, s[10:11] offset:1024
	global_load_dwordx4 v[222:225], v56, s[10:11] offset:2048
	global_load_dwordx4 v[226:229], v56, s[10:11] offset:3072
	global_load_dwordx2 v[230:231], v57, s[10:11]
	global_load_dwordx2 v[232:233], v57, s[10:11] offset:512
	v_cvt_pk_bf16_f32 v8, v0, v1
	v_cvt_pk_bf16_f32 v9, v2, v3
	v_cvt_pk_bf16_f32 v10, v4, v5
	v_cvt_pk_bf16_f32 v11, v6, v7
	ds_write_b64 v64, v[8:9] offset:0
	ds_write_b64 v64, v[10:11] offset:4096
	s_waitcnt lgkmcnt(0)
	s_barrier
	global_store_dwordx2 v58, v[8:9], s[4:5]
	global_store_dwordx2 v59, v[10:11], s[4:5]
	ds_read_b32 v12, v65 offset:16400
	ds_read_b128 v[24:27], v60 offset:0
	ds_read_b128 v[28:31], v60 offset:4096
	ds_read_b128 v[32:35], v61 offset:0
	ds_read_b128 v[36:39], v61 offset:4096
	ds_read_b128 v[40:43], v62 offset:0
	ds_read_b128 v[44:47], v62 offset:4096
	ds_read_b128 v[48:51], v63 offset:0
	ds_read_b128 v[52:55], v63 offset:4096
	s_add_u32 s4, s4, 0x20000
	s_addc_u32 s5, s5, 0
	s_waitcnt vmcnt(58)
	v_lshlrev_b32_e32 v14, 16, v250
	v_and_b32_e32 v15, 0xffff0000, v250
	v_lshlrev_b32_e32 v16, 16, v251
	v_and_b32_e32 v17, 0xffff0000, v251
	v_lshlrev_b32_e32 v18, 16, v252
	v_and_b32_e32 v19, 0xffff0000, v252
	v_lshlrev_b32_e32 v20, 16, v253
	v_and_b32_e32 v21, 0xffff0000, v253
	s_waitcnt lgkmcnt(8)
	v_pk_fma_f32 v[0:1], v[0:1], v[12:13], v[14:15] op_sel_hi:[1,0,1]
	v_pk_fma_f32 v[2:3], v[2:3], v[12:13], v[16:17] op_sel_hi:[1,0,1]
	v_pk_fma_f32 v[4:5], v[4:5], v[12:13], v[18:19] op_sel_hi:[1,0,1]
	v_pk_fma_f32 v[6:7], v[6:7], v[12:13], v[20:21] op_sel_hi:[1,0,1]
	s_waitcnt lgkmcnt(7)
	v_mfma_f32_16x16x32_bf16 v[0:3], v[234:237], v[24:27], v[0:3]
	s_waitcnt lgkmcnt(6)
	v_mfma_f32_16x16x32_bf16 v[4:7], v[234:237], v[28:31], v[4:7]
	s_waitcnt lgkmcnt(5)
	v_mfma_f32_16x16x32_bf16 v[0:3], v[238:241], v[32:35], v[0:3]
	s_waitcnt lgkmcnt(4)
	v_mfma_f32_16x16x32_bf16 v[4:7], v[238:241], v[36:39], v[4:7]
	s_waitcnt lgkmcnt(3)
	v_mfma_f32_16x16x32_bf16 v[0:3], v[242:245], v[40:43], v[0:3]
	s_waitcnt lgkmcnt(2)
	v_mfma_f32_16x16x32_bf16 v[4:7], v[242:245], v[44:47], v[4:7]
	s_waitcnt lgkmcnt(1)
	v_mfma_f32_16x16x32_bf16 v[0:3], v[246:249], v[48:51], v[0:3]
	s_waitcnt lgkmcnt(0)
	v_mfma_f32_16x16x32_bf16 v[4:7], v[246:249], v[52:55], v[4:7]
	s_add_u32 s7, s6, 12
	s_min_u32 s7, s7, 0x80
	s_mul_i32 s7, s7, 0x60000
	s_add_u32 s10, s2, s7
	s_addc_u32 s11, s3, 0
	global_load_dwordx4 v[234:237], v56, s[10:11] offset:0
	global_load_dwordx4 v[238:241], v56, s[10:11] offset:1024
	global_load_dwordx4 v[242:245], v56, s[10:11] offset:2048
	global_load_dwordx4 v[246:249], v56, s[10:11] offset:3072
	global_load_dwordx2 v[250:251], v57, s[10:11]
	global_load_dwordx2 v[252:253], v57, s[10:11] offset:512
	v_cvt_pk_bf16_f32 v8, v0, v1
	v_cvt_pk_bf16_f32 v9, v2, v3
	v_cvt_pk_bf16_f32 v10, v4, v5
	v_cvt_pk_bf16_f32 v11, v6, v7
	ds_write_b64 v64, v[8:9] offset:8192
	ds_write_b64 v64, v[10:11] offset:12288
	s_waitcnt lgkmcnt(0)
	s_barrier
	global_store_dwordx2 v58, v[8:9], s[4:5]
	global_store_dwordx2 v59, v[10:11], s[4:5]
	ds_read_b32 v12, v65 offset:16404
	ds_read_b128 v[24:27], v60 offset:8192
	ds_read_b128 v[28:31], v60 offset:12288
	ds_read_b128 v[32:35], v61 offset:8192
	ds_read_b128 v[36:39], v61 offset:12288
	ds_read_b128 v[40:43], v62 offset:8192
	ds_read_b128 v[44:47], v62 offset:12288
	ds_read_b128 v[48:51], v63 offset:8192
	ds_read_b128 v[52:55], v63 offset:12288
	s_add_u32 s4, s4, 0x20000
	s_addc_u32 s5, s5, 0
	s_waitcnt vmcnt(58)
	v_lshlrev_b32_e32 v14, 16, v106
	v_and_b32_e32 v15, 0xffff0000, v106
	v_lshlrev_b32_e32 v16, 16, v107
	v_and_b32_e32 v17, 0xffff0000, v107
	v_lshlrev_b32_e32 v18, 16, v108
	v_and_b32_e32 v19, 0xffff0000, v108
	v_lshlrev_b32_e32 v20, 16, v109
	v_and_b32_e32 v21, 0xffff0000, v109
	s_waitcnt lgkmcnt(8)
	v_pk_fma_f32 v[0:1], v[0:1], v[12:13], v[14:15] op_sel_hi:[1,0,1]
	v_pk_fma_f32 v[2:3], v[2:3], v[12:13], v[16:17] op_sel_hi:[1,0,1]
	v_pk_fma_f32 v[4:5], v[4:5], v[12:13], v[18:19] op_sel_hi:[1,0,1]
	v_pk_fma_f32 v[6:7], v[6:7], v[12:13], v[20:21] op_sel_hi:[1,0,1]
	s_waitcnt lgkmcnt(7)
	v_mfma_f32_16x16x32_bf16 v[0:3], v[90:93], v[24:27], v[0:3]
	s_waitcnt lgkmcnt(6)
	v_mfma_f32_16x16x32_bf16 v[4:7], v[90:93], v[28:31], v[4:7]
	s_waitcnt lgkmcnt(5)
	v_mfma_f32_16x16x32_bf16 v[0:3], v[94:97], v[32:35], v[0:3]
	s_waitcnt lgkmcnt(4)
	v_mfma_f32_16x16x32_bf16 v[4:7], v[94:97], v[36:39], v[4:7]
	s_waitcnt lgkmcnt(3)
	v_mfma_f32_16x16x32_bf16 v[0:3], v[98:101], v[40:43], v[0:3]
	s_waitcnt lgkmcnt(2)
	v_mfma_f32_16x16x32_bf16 v[4:7], v[98:101], v[44:47], v[4:7]
	s_waitcnt lgkmcnt(1)
	v_mfma_f32_16x16x32_bf16 v[0:3], v[102:105], v[48:51], v[0:3]
	s_waitcnt lgkmcnt(0)
	v_mfma_f32_16x16x32_bf16 v[4:7], v[102:105], v[52:55], v[4:7]
	s_add_u32 s7, s6, 13
	s_min_u32 s7, s7, 0x80
	s_mul_i32 s7, s7, 0x60000
	s_add_u32 s10, s2, s7
	s_addc_u32 s11, s3, 0
	global_load_dwordx4 v[90:93], v56, s[10:11] offset:0
	global_load_dwordx4 v[94:97], v56, s[10:11] offset:1024
	global_load_dwordx4 v[98:101], v56, s[10:11] offset:2048
	global_load_dwordx4 v[102:105], v56, s[10:11] offset:3072
	global_load_dwordx2 v[106:107], v57, s[10:11]
	global_load_dwordx2 v[108:109], v57, s[10:11] offset:512
	v_cvt_pk_bf16_f32 v8, v0, v1
	v_cvt_pk_bf16_f32 v9, v2, v3
	v_cvt_pk_bf16_f32 v10, v4, v5
	v_cvt_pk_bf16_f32 v11, v6, v7
	ds_write_b64 v64, v[8:9] offset:0
	ds_write_b64 v64, v[10:11] offset:4096
	s_waitcnt lgkmcnt(0)
	s_barrier
	global_store_dwordx2 v58, v[8:9], s[4:5]
	global_store_dwordx2 v59, v[10:11], s[4:5]
	ds_read_b32 v12, v65 offset:16408
	ds_read_b128 v[24:27], v60 offset:0
	ds_read_b128 v[28:31], v60 offset:4096
	ds_read_b128 v[32:35], v61 offset:0
	ds_read_b128 v[36:39], v61 offset:4096
	ds_read_b128 v[40:43], v62 offset:0
	ds_read_b128 v[44:47], v62 offset:4096
	ds_read_b128 v[48:51], v63 offset:0
	ds_read_b128 v[52:55], v63 offset:4096
	s_add_u32 s4, s4, 0x20000
	s_addc_u32 s5, s5, 0
	s_waitcnt vmcnt(58)
	v_lshlrev_b32_e32 v14, 16, v126
	v_and_b32_e32 v15, 0xffff0000, v126
	v_lshlrev_b32_e32 v16, 16, v127
	v_and_b32_e32 v17, 0xffff0000, v127
	v_lshlrev_b32_e32 v18, 16, v128
	v_and_b32_e32 v19, 0xffff0000, v128
	v_lshlrev_b32_e32 v20, 16, v129
	v_and_b32_e32 v21, 0xffff0000, v129
	s_waitcnt lgkmcnt(8)
	v_pk_fma_f32 v[0:1], v[0:1], v[12:13], v[14:15] op_sel_hi:[1,0,1]
	v_pk_fma_f32 v[2:3], v[2:3], v[12:13], v[16:17] op_sel_hi:[1,0,1]
	v_pk_fma_f32 v[4:5], v[4:5], v[12:13], v[18:19] op_sel_hi:[1,0,1]
	v_pk_fma_f32 v[6:7], v[6:7], v[12:13], v[20:21] op_sel_hi:[1,0,1]
	s_waitcnt lgkmcnt(7)
	v_mfma_f32_16x16x32_bf16 v[0:3], v[110:113], v[24:27], v[0:3]
	s_waitcnt lgkmcnt(6)
	v_mfma_f32_16x16x32_bf16 v[4:7], v[110:113], v[28:31], v[4:7]
	s_waitcnt lgkmcnt(5)
	v_mfma_f32_16x16x32_bf16 v[0:3], v[114:117], v[32:35], v[0:3]
	s_waitcnt lgkmcnt(4)
	v_mfma_f32_16x16x32_bf16 v[4:7], v[114:117], v[36:39], v[4:7]
	s_waitcnt lgkmcnt(3)
	v_mfma_f32_16x16x32_bf16 v[0:3], v[118:121], v[40:43], v[0:3]
	s_waitcnt lgkmcnt(2)
	v_mfma_f32_16x16x32_bf16 v[4:7], v[118:121], v[44:47], v[4:7]
	s_waitcnt lgkmcnt(1)
	v_mfma_f32_16x16x32_bf16 v[0:3], v[122:125], v[48:51], v[0:3]
	s_waitcnt lgkmcnt(0)
	v_mfma_f32_16x16x32_bf16 v[4:7], v[122:125], v[52:55], v[4:7]
	s_add_u32 s7, s6, 14
	s_min_u32 s7, s7, 0x80
	s_mul_i32 s7, s7, 0x60000
	s_add_u32 s10, s2, s7
	s_addc_u32 s11, s3, 0
	global_load_dwordx4 v[110:113], v56, s[10:11] offset:0
	global_load_dwordx4 v[114:117], v56, s[10:11] offset:1024
	global_load_dwordx4 v[118:121], v56, s[10:11] offset:2048
	global_load_dwordx4 v[122:125], v56, s[10:11] offset:3072
	global_load_dwordx2 v[126:127], v57, s[10:11]
	global_load_dwordx2 v[128:129], v57, s[10:11] offset:512
	v_cvt_pk_bf16_f32 v8, v0, v1
	v_cvt_pk_bf16_f32 v9, v2, v3
	v_cvt_pk_bf16_f32 v10, v4, v5
	v_cvt_pk_bf16_f32 v11, v6, v7
	ds_write_b64 v64, v[8:9] offset:8192
	ds_write_b64 v64, v[10:11] offset:12288
	s_waitcnt lgkmcnt(0)
	s_barrier
	global_store_dwordx2 v58, v[8:9], s[4:5]
	global_store_dwordx2 v59, v[10:11], s[4:5]
	ds_read_b32 v12, v65 offset:16412
	ds_read_b128 v[24:27], v60 offset:8192
	ds_read_b128 v[28:31], v60 offset:12288
	ds_read_b128 v[32:35], v61 offset:8192
	ds_read_b128 v[36:39], v61 offset:12288
	ds_read_b128 v[40:43], v62 offset:8192
	ds_read_b128 v[44:47], v62 offset:12288
	ds_read_b128 v[48:51], v63 offset:8192
	ds_read_b128 v[52:55], v63 offset:12288
	s_add_u32 s4, s4, 0x20000
	s_addc_u32 s5, s5, 0
	s_waitcnt vmcnt(58)
	v_lshlrev_b32_e32 v14, 16, v146
	v_and_b32_e32 v15, 0xffff0000, v146
	v_lshlrev_b32_e32 v16, 16, v147
	v_and_b32_e32 v17, 0xffff0000, v147
	v_lshlrev_b32_e32 v18, 16, v148
	v_and_b32_e32 v19, 0xffff0000, v148
	v_lshlrev_b32_e32 v20, 16, v149
	v_and_b32_e32 v21, 0xffff0000, v149
	s_waitcnt lgkmcnt(8)
	v_pk_fma_f32 v[0:1], v[0:1], v[12:13], v[14:15] op_sel_hi:[1,0,1]
	v_pk_fma_f32 v[2:3], v[2:3], v[12:13], v[16:17] op_sel_hi:[1,0,1]
	v_pk_fma_f32 v[4:5], v[4:5], v[12:13], v[18:19] op_sel_hi:[1,0,1]
	v_pk_fma_f32 v[6:7], v[6:7], v[12:13], v[20:21] op_sel_hi:[1,0,1]
	s_waitcnt lgkmcnt(7)
	v_mfma_f32_16x16x32_bf16 v[0:3], v[130:133], v[24:27], v[0:3]
	s_waitcnt lgkmcnt(6)
	v_mfma_f32_16x16x32_bf16 v[4:7], v[130:133], v[28:31], v[4:7]
	s_waitcnt lgkmcnt(5)
	v_mfma_f32_16x16x32_bf16 v[0:3], v[134:137], v[32:35], v[0:3]
	s_waitcnt lgkmcnt(4)
	v_mfma_f32_16x16x32_bf16 v[4:7], v[134:137], v[36:39], v[4:7]
	s_waitcnt lgkmcnt(3)
	v_mfma_f32_16x16x32_bf16 v[0:3], v[138:141], v[40:43], v[0:3]
	s_waitcnt lgkmcnt(2)
	v_mfma_f32_16x16x32_bf16 v[4:7], v[138:141], v[44:47], v[4:7]
	s_waitcnt lgkmcnt(1)
	v_mfma_f32_16x16x32_bf16 v[0:3], v[142:145], v[48:51], v[0:3]
	s_waitcnt lgkmcnt(0)
	v_mfma_f32_16x16x32_bf16 v[4:7], v[142:145], v[52:55], v[4:7]
	s_add_u32 s7, s6, 15
	s_min_u32 s7, s7, 0x80
	s_mul_i32 s7, s7, 0x60000
	s_add_u32 s10, s2, s7
	s_addc_u32 s11, s3, 0
	global_load_dwordx4 v[130:133], v56, s[10:11] offset:0
	global_load_dwordx4 v[134:137], v56, s[10:11] offset:1024
	global_load_dwordx4 v[138:141], v56, s[10:11] offset:2048
	global_load_dwordx4 v[142:145], v56, s[10:11] offset:3072
	global_load_dwordx2 v[146:147], v57, s[10:11]
	global_load_dwordx2 v[148:149], v57, s[10:11] offset:512
	v_cvt_pk_bf16_f32 v8, v0, v1
	v_cvt_pk_bf16_f32 v9, v2, v3
	v_cvt_pk_bf16_f32 v10, v4, v5
	v_cvt_pk_bf16_f32 v11, v6, v7
	ds_write_b64 v64, v[8:9] offset:0
	ds_write_b64 v64, v[10:11] offset:4096
	s_add_u32 s6, s6, 8
	v_add_u32_e32 v65, 32, v65
	s_cmp_lt_u32 s6, 128
	s_cbranch_scc1 .Ldnch_loop_l1
	s_waitcnt lgkmcnt(0)
	s_barrier
	global_store_dwordx2 v58, v[8:9], s[4:5]
	global_store_dwordx2 v59, v[10:11], s[4:5]
	ds_read_b32 v12, v65 offset:16384
	ds_read_b128 v[24:27], v60 offset:0
	ds_read_b128 v[28:31], v60 offset:4096
	ds_read_b128 v[32:35], v61 offset:0
	ds_read_b128 v[36:39], v61 offset:4096
	ds_read_b128 v[40:43], v62 offset:0
	ds_read_b128 v[44:47], v62 offset:4096
	ds_read_b128 v[48:51], v63 offset:0
	ds_read_b128 v[52:55], v63 offset:4096
	s_add_u32 s4, s4, 0x20000
	s_addc_u32 s5, s5, 0
	s_waitcnt vmcnt(58)
	v_lshlrev_b32_e32 v14, 16, v170
	v_and_b32_e32 v15, 0xffff0000, v170
	v_lshlrev_b32_e32 v16, 16, v171
	v_and_b32_e32 v17, 0xffff0000, v171
	v_lshlrev_b32_e32 v18, 16, v172
	v_and_b32_e32 v19, 0xffff0000, v172
	v_lshlrev_b32_e32 v20, 16, v173
	v_and_b32_e32 v21, 0xffff0000, v173
	s_waitcnt lgkmcnt(8)
	v_pk_fma_f32 v[0:1], v[0:1], v[12:13], v[14:15] op_sel_hi:[1,0,1]
	v_pk_fma_f32 v[2:3], v[2:3], v[12:13], v[16:17] op_sel_hi:[1,0,1]
	v_pk_fma_f32 v[4:5], v[4:5], v[12:13], v[18:19] op_sel_hi:[1,0,1]
	v_pk_fma_f32 v[6:7], v[6:7], v[12:13], v[20:21] op_sel_hi:[1,0,1]
	s_waitcnt lgkmcnt(7)
	v_mfma_f32_16x16x32_bf16 v[0:3], v[154:157], v[24:27], v[0:3]
	s_waitcnt lgkmcnt(6)
	v_mfma_f32_16x16x32_bf16 v[4:7], v[154:157], v[28:31], v[4:7]
	s_waitcnt lgkmcnt(5)
	v_mfma_f32_16x16x32_bf16 v[0:3], v[158:161], v[32:35], v[0:3]
	s_waitcnt lgkmcnt(4)
	v_mfma_f32_16x16x32_bf16 v[4:7], v[158:161], v[36:39], v[4:7]
	s_waitcnt lgkmcnt(3)
	v_mfma_f32_16x16x32_bf16 v[0:3], v[162:165], v[40:43], v[0:3]
	s_waitcnt lgkmcnt(2)
	v_mfma_f32_16x16x32_bf16 v[4:7], v[162:165], v[44:47], v[4:7]
	s_waitcnt lgkmcnt(1)
	v_mfma_f32_16x16x32_bf16 v[0:3], v[166:169], v[48:51], v[0:3]
	s_waitcnt lgkmcnt(0)
	v_mfma_f32_16x16x32_bf16 v[4:7], v[166:169], v[52:55], v[4:7]
	s_nop 7
	s_nop 1
	v_cvt_pk_bf16_f32 v8, v0, v1
	v_cvt_pk_bf16_f32 v9, v2, v3
	v_cvt_pk_bf16_f32 v10, v4, v5
	v_cvt_pk_bf16_f32 v11, v6, v7
	ds_write_b64 v64, v[8:9] offset:8192
	ds_write_b64 v64, v[10:11] offset:12288
	s_lshl_b32 s14, s13, 16
	s_add_u32 s16, s20, s14
	s_addc_u32 s17, s21, 0
	s_add_u32 s16, s16, 0x4480000
	s_addc_u32 s17, s17, 0
	v_and_b32_e32 v68, 15, v66
	v_lshrrev_b32_e32 v69, 4, v66
	v_lshlrev_b32_e32 v70, 2, v69
	s_lshl_b32 s14, s0, 4
	v_add_u32_e32 v70, s14, v70
	v_lshlrev_b32_e32 v70, 7, v70
	s_and_b32 s14, s1, 31
	s_lshl_b32 s14, s14, 5
	v_add3_u32 v70, v70, s14, v68
	v_lshlrev_b32_e32 v70, 2, v70
	global_store_dword v70, v0, s[16:17] offset:0
	global_store_dword v70, v1, s[16:17] offset:512
	global_store_dword v70, v2, s[16:17] offset:1024
	global_store_dword v70, v3, s[16:17] offset:1536
	global_store_dword v70, v4, s[16:17] offset:64
	global_store_dword v70, v5, s[16:17] offset:576
	global_store_dword v70, v6, s[16:17] offset:1088
	global_store_dword v70, v7, s[16:17] offset:1600
	s_waitcnt vmcnt(0) lgkmcnt(0)
	s_barrier
	s_branch .LBB0_2078
